# v40 + waves 0-3 run the swiglu epilogue at priority 1 (they reach the next unit's first barrier last), reset after the stores
# baseline (speedup 1.0000x reference)
; __device__ __forceinline__ unsigned cvt_pk_bf16(float lo, float hi) { unsigned r; asm volatile("v_cvt_pk_bf16_f32 %0, %1, %2" : "=v"(r) : "v"(lo), "v"(hi)); return r; }
; __device__ __forceinline__ float row_rstd(const float* ss, int row) { return 1.0f / sqrtf(ss[row] * (1.0f / DM) + 1e-6f); }
; __device__ __forceinline__ float silu_mul(float a, float b) { return a * b * __builtin_amdgcn_rcpf(1.0f + __builtin_amdgcn_exp2f(-a * LOG2E)); }
; #define PG8_BAR __builtin_amdgcn_s_barrier()
;     __device__ __forceinline__ void operator()(const f32x4 (&acc)[2][2][4][2], const Unit& u, int wr, int wc, int fr, int fq) const {
;         const int row0 = u.pm * BM + wr * 64 + fr, col0 = u.pn * HALF + wc * 32 + 8 * fq;
;         const int s = (u.pm < ML / BM) ? (u.pm >> 5) : 4;
;         const float* bp = bias + (size_t)s * BIAS_N + u.pn * BM + wc * 32 + 8 * fq;
;         const f32x4 ba0 = *(const f32x4*)bp, ba1 = *(const f32x4*)(bp + 4), bb0 = *(const f32x4*)(bp + HALF), bb1 = *(const f32x4*)(bp + HALF + 4);
;         const int lane = fq * 16 + fr;
;         const float rsl0 = row_rstd(ss, u.pm * BM + wr * 64 + lane), rsl1 = row_rstd(ss, u.pm * BM + HALF + wr * 64 + lane);
; #pragma unroll
;         for (int ai = 0; ai < 2; ++ai)
; #pragma unroll
;             for (int m = 0; m < 4; ++m) { const int row = row0 + ai * HALF + m * 16; const float rs = __shfl(ai ? rsl1 : rsl0, m * 16 + fr); bf16_t* rowp = O + (size_t)row * DFF + col0;
;                 const f32x4 a0 = acc[ai][0][m][0] * rs + ba0, a1 = acc[ai][0][m][1] * rs + ba1, b0 = acc[ai][1][m][0] * rs + bb0, b1 = acc[ai][1][m][1] * rs + bb1;
;                 u32x4 w; w.x = cvt_pk_bf16(silu_mul(a0[0], b0[0]), silu_mul(a0[1], b0[1])); w.y = cvt_pk_bf16(silu_mul(a0[2], b0[2]), silu_mul(a0[3], b0[3]));
;                 w.z = cvt_pk_bf16(silu_mul(a1[0], b1[0]), silu_mul(a1[1], b1[1])); w.w = cvt_pk_bf16(silu_mul(a1[2], b1[2]), silu_mul(a1[3], b1[3]));
;                 *(u32x4*)rowp = w; }
; template <class Epi, class Sched, bool ALIGN_EPI = false, bool SP2 = false>
; __device__ __forceinline__ void gemm_phase(LAS unsigned char* lds, const Gemm g, const Sched& S, const Epi& E) {
;     ...
;         if constexpr (ALIGN_EPI) { if (wr == 0) PG8_BAR; }
;         if constexpr (!Epi::AFTER_DRAIN) { E(acc, cur, wr, wc, fr, fq); S.done(cur); }
.LBB0_193:
	s_lshl_b32 s2, s2, 8
	s_add_i32 s12, s2, s54
	s_lshl_b64 s[2:3], s[16:17], 2
	s_add_u32 s13, s68, s2
	s_addc_u32 s14, s69, s3
	s_lshl_b32 s2, s0, 8
	s_ashr_i32 s3, s2, 31
	s_lshl_b64 s[2:3], s[2:3], 2
	v_lshl_or_b32 v164, s0, 7, v173
	s_add_u32 s0, s13, s2
	s_addc_u32 s3, s14, s3
	v_or_b32_e32 v162, s12, v171
	s_add_u32 s2, s0, s60
	v_ashrrev_i32_e32 v163, 31, v162
	s_addc_u32 s3, s3, 0
	v_lshl_add_u64 v[162:163], v[162:163], 2, s[8:9]
	v_mov_b32_e32 v74, v234
	v_mov_b32_e32 v75, v235
	v_mov_b32_e32 v76, v236
	v_mov_b32_e32 v77, v237
	v_mov_b32_e32 v78, v238
	v_mov_b32_e32 v79, v239
	v_mov_b32_e32 v80, v240
	v_mov_b32_e32 v81, v241
	v_mov_b32_e32 v66, v242
	v_mov_b32_e32 v67, v243
	v_mov_b32_e32 v68, v244
	v_mov_b32_e32 v69, v245
	v_mov_b32_e32 v70, v246
	v_mov_b32_e32 v71, v247
	v_mov_b32_e32 v72, v248
	v_mov_b32_e32 v73, v249
	v_or_b32_e32 v181, s12, v169
	v_mov_b32_e32 v162, v250
	v_fmamk_f32 v162, v162, 0x3a000000, v178
	v_cmp_gt_f32_e32 vcc, s61, v162
	v_mul_f32_e32 v163, 0x4f800000, v162
	s_nop 0
	v_cndmask_b32_e32 v162, v162, v163, vcc
	v_sqrt_f32_e32 v163, v162
	s_nop 0
	v_add_u32_e32 v165, -1, v163
	v_fma_f32 v166, -v165, v163, v162
	v_cmp_ge_f32_e64 s[2:3], 0, v166
	v_add_u32_e32 v166, 1, v163
	s_nop 0
	v_cndmask_b32_e64 v165, v163, v165, s[2:3]
	v_fma_f32 v163, -v166, v163, v162
	v_cmp_lt_f32_e64 s[2:3], 0, v163
	s_nop 1
	v_cndmask_b32_e64 v163, v165, v166, s[2:3]
	v_mul_f32_e32 v165, 0x37800000, v163
	v_cndmask_b32_e32 v163, v163, v165, vcc
	v_cmp_class_f32_e32 vcc, v162, v179
	s_nop 1
	v_cndmask_b32_e32 v166, v163, v162, vcc
	v_add_u32_e32 v162, s12, v172
	v_ashrrev_i32_e32 v163, 31, v162
	v_lshl_add_u64 v[162:163], v[162:163], 2, s[8:9]
	v_mov_b32_e32 v162, v251
	v_fmamk_f32 v162, v162, 0x3a000000, v178
	v_cmp_gt_f32_e32 vcc, s61, v162
	v_mul_f32_e32 v163, 0x4f800000, v162
	s_nop 0
	v_cndmask_b32_e32 v162, v162, v163, vcc
	v_sqrt_f32_e32 v163, v162
	s_nop 0
	v_add_u32_e32 v165, -1, v163
	v_fma_f32 v167, -v165, v163, v162
	v_cmp_ge_f32_e64 s[2:3], 0, v167
	v_add_u32_e32 v167, 1, v163
	s_nop 0
	v_cndmask_b32_e64 v165, v163, v165, s[2:3]
	v_fma_f32 v163, -v167, v163, v162
	v_cmp_lt_f32_e64 s[2:3], 0, v163
	s_nop 1
	v_cndmask_b32_e64 v163, v165, v167, s[2:3]
	v_mul_f32_e32 v165, 0x37800000, v163
	v_cndmask_b32_e32 v163, v163, v165, vcc
	v_cmp_class_f32_e32 vcc, v162, v179
	v_ashrrev_i32_e32 v165, 31, v164
	v_lshlrev_b64 v[164:165], 1, v[164:165]
	v_cndmask_b32_e32 v182, v163, v162, vcc
	v_div_scale_f32 v162, s[2:3], v166, v166, 1.0
	v_rcp_f32_e32 v163, v162
	s_nop 0
	v_fma_f32 v167, -v162, v163, 1.0
	v_fmac_f32_e32 v163, v167, v163
	v_div_scale_f32 v167, vcc, 1.0, v166, 1.0
	v_mul_f32_e32 v168, v167, v163
	v_fma_f32 v183, -v162, v168, v167
	v_fmac_f32_e32 v168, v183, v163
	v_fma_f32 v162, -v162, v168, v167
	v_div_fmas_f32 v162, v162, v163, v168
	v_div_fixup_f32 v183, v162, v166, 1.0
	s_and_b64 vcc, exec, s[40:41]
	s_cbranch_vccz .Lalign_191
	s_barrier
	s_setprio 1
.Lalign_191:
	s_mov_b32 s100, 0xbfb8aa3b
	ds_bpermute_b32 v242, v180, v183
	ds_bpermute_b32 v244, v180, v183 offset:64
	ds_bpermute_b32 v246, v180, v183 offset:128
	ds_bpermute_b32 v248, v180, v183 offset:192
	v_mov_b64_e32 v[162:163], s[96:97]
	v_mad_i64_i32 v[166:167], s[2:3], v181, s59, v[162:163]
	v_lshl_add_u64 v[166:167], v[166:167], 0, v[164:165]
	s_waitcnt lgkmcnt(0)
	v_pk_fma_f32 v[142:143], v[142:143], v[242:243], v[78:79] op_sel_hi:[1,0,1]
	v_pk_fma_f32 v[144:145], v[144:145], v[242:243], v[80:81] op_sel_hi:[1,0,1]
	v_pk_fma_f32 v[134:135], v[134:135], v[242:243], v[70:71] op_sel_hi:[1,0,1]
	v_pk_fma_f32 v[136:137], v[136:137], v[242:243], v[72:73] op_sel_hi:[1,0,1]
	v_pk_fma_f32 v[138:139], v[138:139], v[242:243], v[74:75] op_sel_hi:[1,0,1]
	v_pk_fma_f32 v[140:141], v[140:141], v[242:243], v[76:77] op_sel_hi:[1,0,1]
	v_pk_fma_f32 v[130:131], v[130:131], v[242:243], v[66:67] op_sel_hi:[1,0,1]
	v_pk_fma_f32 v[132:133], v[132:133], v[242:243], v[68:69] op_sel_hi:[1,0,1]
	v_pk_mul_f32 v[234:235], v[142:143], s[100:101] op_sel_hi:[1,0]
	v_pk_mul_f32 v[236:237], v[144:145], s[100:101] op_sel_hi:[1,0]
	v_exp_f32_e32 v234, v234
	v_exp_f32_e32 v235, v235
	v_exp_f32_e32 v236, v236
	v_exp_f32_e32 v237, v237
	v_pk_add_f32 v[234:235], v[234:235], 1.0 op_sel_hi:[1,0]
	v_pk_add_f32 v[236:237], v[236:237], 1.0 op_sel_hi:[1,0]
	v_rcp_f32_e32 v234, v234
	v_rcp_f32_e32 v235, v235
	v_rcp_f32_e32 v236, v236
	v_rcp_f32_e32 v237, v237
	v_pk_mul_f32 v[134:135], v[142:143], v[134:135]
	v_pk_mul_f32 v[136:137], v[144:145], v[136:137]
	v_pk_mul_f32 v[134:135], v[134:135], v[234:235]
	v_pk_mul_f32 v[136:137], v[136:137], v[236:237]
	v_cvt_pk_bf16_f32 v238, v134, v135
	v_cvt_pk_bf16_f32 v239, v136, v137
	v_pk_mul_f32 v[234:235], v[138:139], s[100:101] op_sel_hi:[1,0]
	v_pk_mul_f32 v[236:237], v[140:141], s[100:101] op_sel_hi:[1,0]
	v_exp_f32_e32 v234, v234
	v_exp_f32_e32 v235, v235
	v_exp_f32_e32 v236, v236
	v_exp_f32_e32 v237, v237
	v_pk_add_f32 v[234:235], v[234:235], 1.0 op_sel_hi:[1,0]
	v_pk_add_f32 v[236:237], v[236:237], 1.0 op_sel_hi:[1,0]
	v_rcp_f32_e32 v234, v234
	v_rcp_f32_e32 v235, v235
	v_rcp_f32_e32 v236, v236
	v_rcp_f32_e32 v237, v237
	v_pk_mul_f32 v[130:131], v[138:139], v[130:131]
	v_pk_mul_f32 v[132:133], v[140:141], v[132:133]
	v_pk_mul_f32 v[130:131], v[130:131], v[234:235]
	v_pk_mul_f32 v[132:133], v[132:133], v[236:237]
	v_cvt_pk_bf16_f32 v240, v130, v131
	v_cvt_pk_bf16_f32 v241, v132, v133
	global_store_dwordx4 v[166:167], v[238:241], off
	v_or_b32_e32 v131, 16, v181
	v_mad_i64_i32 v[132:133], s[2:3], v131, s59, v[162:163]
	v_lshl_add_u64 v[132:133], v[132:133], 0, v[164:165]
	v_pk_fma_f32 v[126:127], v[126:127], v[244:245], v[78:79] op_sel_hi:[1,0,1]
; __device__ __forceinline__ unsigned cvt_pk_bf16(float lo, float hi) { unsigned r; asm volatile("v_cvt_pk_bf16_f32 %0, %1, %2" : "=v"(r) : "v"(lo), "v"(hi)); return r; }
; __device__ __forceinline__ float silu_mul(float a, float b) { return a * b * __builtin_amdgcn_rcpf(1.0f + __builtin_amdgcn_exp2f(-a * LOG2E)); }
;     __device__ __forceinline__ void operator()(const f32x4 (&acc)[2][2][4][2], const Unit& u, int wr, int wc, int fr, int fq) const {
;     ...
;             for (int m = 0; m < 4; ++m) { const int row = row0 + ai * HALF + m * 16; const float rs = __shfl(ai ? rsl1 : rsl0, m * 16 + fr); bf16_t* rowp = O + (size_t)row * DFF + col0;
;                 const f32x4 a0 = acc[ai][0][m][0] * rs + ba0, a1 = acc[ai][0][m][1] * rs + ba1, b0 = acc[ai][1][m][0] * rs + bb0, b1 = acc[ai][1][m][1] * rs + bb1;
;                 u32x4 w; w.x = cvt_pk_bf16(silu_mul(a0[0], b0[0]), silu_mul(a0[1], b0[1])); w.y = cvt_pk_bf16(silu_mul(a0[2], b0[2]), silu_mul(a0[3], b0[3]));
;                 w.z = cvt_pk_bf16(silu_mul(a1[0], b1[0]), silu_mul(a1[1], b1[1])); w.w = cvt_pk_bf16(silu_mul(a1[2], b1[2]), silu_mul(a1[3], b1[3]));
;                 *(u32x4*)rowp = w; }
	v_pk_fma_f32 v[128:129], v[128:129], v[244:245], v[80:81] op_sel_hi:[1,0,1]
	v_pk_fma_f32 v[118:119], v[118:119], v[244:245], v[70:71] op_sel_hi:[1,0,1]
	v_pk_fma_f32 v[120:121], v[120:121], v[244:245], v[72:73] op_sel_hi:[1,0,1]
	v_pk_fma_f32 v[122:123], v[122:123], v[244:245], v[74:75] op_sel_hi:[1,0,1]
	v_pk_fma_f32 v[124:125], v[124:125], v[244:245], v[76:77] op_sel_hi:[1,0,1]
	v_pk_fma_f32 v[114:115], v[114:115], v[244:245], v[66:67] op_sel_hi:[1,0,1]
	v_pk_fma_f32 v[116:117], v[116:117], v[244:245], v[68:69] op_sel_hi:[1,0,1]
	v_pk_mul_f32 v[234:235], v[126:127], s[100:101] op_sel_hi:[1,0]
	v_pk_mul_f32 v[236:237], v[128:129], s[100:101] op_sel_hi:[1,0]
	v_exp_f32_e32 v234, v234
	v_exp_f32_e32 v235, v235
	v_exp_f32_e32 v236, v236
	v_exp_f32_e32 v237, v237
	v_pk_add_f32 v[234:235], v[234:235], 1.0 op_sel_hi:[1,0]
	v_pk_add_f32 v[236:237], v[236:237], 1.0 op_sel_hi:[1,0]
	v_rcp_f32_e32 v234, v234
	v_rcp_f32_e32 v235, v235
	v_rcp_f32_e32 v236, v236
	v_rcp_f32_e32 v237, v237
	v_pk_mul_f32 v[118:119], v[126:127], v[118:119]
	v_pk_mul_f32 v[120:121], v[128:129], v[120:121]
	v_pk_mul_f32 v[118:119], v[118:119], v[234:235]
	v_pk_mul_f32 v[120:121], v[120:121], v[236:237]
	v_cvt_pk_bf16_f32 v238, v118, v119
	v_cvt_pk_bf16_f32 v239, v120, v121
	v_pk_mul_f32 v[234:235], v[122:123], s[100:101] op_sel_hi:[1,0]
	v_pk_mul_f32 v[236:237], v[124:125], s[100:101] op_sel_hi:[1,0]
	v_exp_f32_e32 v234, v234
	v_exp_f32_e32 v235, v235
	v_exp_f32_e32 v236, v236
	v_exp_f32_e32 v237, v237
	v_pk_add_f32 v[234:235], v[234:235], 1.0 op_sel_hi:[1,0]
	v_pk_add_f32 v[236:237], v[236:237], 1.0 op_sel_hi:[1,0]
	v_rcp_f32_e32 v234, v234
	v_rcp_f32_e32 v235, v235
	v_rcp_f32_e32 v236, v236
	v_rcp_f32_e32 v237, v237
	v_pk_mul_f32 v[114:115], v[122:123], v[114:115]
	v_pk_mul_f32 v[116:117], v[124:125], v[116:117]
	v_pk_mul_f32 v[114:115], v[114:115], v[234:235]
	v_pk_mul_f32 v[116:117], v[116:117], v[236:237]
	v_cvt_pk_bf16_f32 v240, v114, v115
	v_cvt_pk_bf16_f32 v241, v116, v117
	global_store_dwordx4 v[132:133], v[238:241], off
	v_or_b32_e32 v115, 32, v181
	v_mad_i64_i32 v[116:117], s[2:3], v115, s59, v[162:163]
	v_lshl_add_u64 v[116:117], v[116:117], 0, v[164:165]
	v_pk_fma_f32 v[110:111], v[110:111], v[246:247], v[78:79] op_sel_hi:[1,0,1]
	v_pk_fma_f32 v[112:113], v[112:113], v[246:247], v[80:81] op_sel_hi:[1,0,1]
	v_pk_fma_f32 v[102:103], v[102:103], v[246:247], v[70:71] op_sel_hi:[1,0,1]
	v_pk_fma_f32 v[104:105], v[104:105], v[246:247], v[72:73] op_sel_hi:[1,0,1]
	v_pk_fma_f32 v[106:107], v[106:107], v[246:247], v[74:75] op_sel_hi:[1,0,1]
	v_pk_fma_f32 v[108:109], v[108:109], v[246:247], v[76:77] op_sel_hi:[1,0,1]
	v_pk_fma_f32 v[98:99], v[98:99], v[246:247], v[66:67] op_sel_hi:[1,0,1]
	v_pk_fma_f32 v[100:101], v[100:101], v[246:247], v[68:69] op_sel_hi:[1,0,1]
	v_pk_mul_f32 v[234:235], v[110:111], s[100:101] op_sel_hi:[1,0]
	v_pk_mul_f32 v[236:237], v[112:113], s[100:101] op_sel_hi:[1,0]
	v_exp_f32_e32 v234, v234
	v_exp_f32_e32 v235, v235
	v_exp_f32_e32 v236, v236
	v_exp_f32_e32 v237, v237
	v_pk_add_f32 v[234:235], v[234:235], 1.0 op_sel_hi:[1,0]
	v_pk_add_f32 v[236:237], v[236:237], 1.0 op_sel_hi:[1,0]
	v_rcp_f32_e32 v234, v234
	v_rcp_f32_e32 v235, v235
	v_rcp_f32_e32 v236, v236
	v_rcp_f32_e32 v237, v237
	v_pk_mul_f32 v[102:103], v[110:111], v[102:103]
	v_pk_mul_f32 v[104:105], v[112:113], v[104:105]
	v_pk_mul_f32 v[102:103], v[102:103], v[234:235]
	v_pk_mul_f32 v[104:105], v[104:105], v[236:237]
	v_cvt_pk_bf16_f32 v238, v102, v103
	v_cvt_pk_bf16_f32 v239, v104, v105
	v_pk_mul_f32 v[234:235], v[106:107], s[100:101] op_sel_hi:[1,0]
	v_pk_mul_f32 v[236:237], v[108:109], s[100:101] op_sel_hi:[1,0]
	v_exp_f32_e32 v234, v234
	v_exp_f32_e32 v235, v235
	v_exp_f32_e32 v236, v236
	v_exp_f32_e32 v237, v237
	v_pk_add_f32 v[234:235], v[234:235], 1.0 op_sel_hi:[1,0]
	v_pk_add_f32 v[236:237], v[236:237], 1.0 op_sel_hi:[1,0]
	v_rcp_f32_e32 v234, v234
	v_rcp_f32_e32 v235, v235
	v_rcp_f32_e32 v236, v236
	v_rcp_f32_e32 v237, v237
	v_pk_mul_f32 v[98:99], v[106:107], v[98:99]
	v_pk_mul_f32 v[100:101], v[108:109], v[100:101]
	v_pk_mul_f32 v[98:99], v[98:99], v[234:235]
	v_pk_mul_f32 v[100:101], v[100:101], v[236:237]
	v_cvt_pk_bf16_f32 v240, v98, v99
	v_cvt_pk_bf16_f32 v241, v100, v101
	global_store_dwordx4 v[116:117], v[238:241], off
	v_or_b32_e32 v99, 48, v181
	v_mad_i64_i32 v[100:101], s[2:3], v99, s59, v[162:163]
	v_lshl_add_u64 v[100:101], v[100:101], 0, v[164:165]
	v_pk_fma_f32 v[94:95], v[94:95], v[248:249], v[78:79] op_sel_hi:[1,0,1]
	v_pk_fma_f32 v[96:97], v[96:97], v[248:249], v[80:81] op_sel_hi:[1,0,1]
	v_pk_fma_f32 v[86:87], v[86:87], v[248:249], v[70:71] op_sel_hi:[1,0,1]
	v_pk_fma_f32 v[88:89], v[88:89], v[248:249], v[72:73] op_sel_hi:[1,0,1]
	v_pk_fma_f32 v[90:91], v[90:91], v[248:249], v[74:75] op_sel_hi:[1,0,1]
	v_pk_fma_f32 v[92:93], v[92:93], v[248:249], v[76:77] op_sel_hi:[1,0,1]
	v_pk_fma_f32 v[82:83], v[82:83], v[248:249], v[66:67] op_sel_hi:[1,0,1]
	v_pk_fma_f32 v[84:85], v[84:85], v[248:249], v[68:69] op_sel_hi:[1,0,1]
	v_pk_mul_f32 v[234:235], v[94:95], s[100:101] op_sel_hi:[1,0]
	v_pk_mul_f32 v[236:237], v[96:97], s[100:101] op_sel_hi:[1,0]
	v_exp_f32_e32 v234, v234
	v_exp_f32_e32 v235, v235
	v_exp_f32_e32 v236, v236
	v_exp_f32_e32 v237, v237
	v_pk_add_f32 v[234:235], v[234:235], 1.0 op_sel_hi:[1,0]
	v_pk_add_f32 v[236:237], v[236:237], 1.0 op_sel_hi:[1,0]
	v_rcp_f32_e32 v234, v234
	v_rcp_f32_e32 v235, v235
	v_rcp_f32_e32 v236, v236
	v_rcp_f32_e32 v237, v237
	v_pk_mul_f32 v[86:87], v[94:95], v[86:87]
	v_pk_mul_f32 v[88:89], v[96:97], v[88:89]
	v_pk_mul_f32 v[86:87], v[86:87], v[234:235]
	v_pk_mul_f32 v[88:89], v[88:89], v[236:237]
	v_cvt_pk_bf16_f32 v238, v86, v87
; __device__ __forceinline__ unsigned cvt_pk_bf16(float lo, float hi) { unsigned r; asm volatile("v_cvt_pk_bf16_f32 %0, %1, %2" : "=v"(r) : "v"(lo), "v"(hi)); return r; }
; __device__ __forceinline__ float row_rstd(const float* ss, int row) { return 1.0f / sqrtf(ss[row] * (1.0f / DM) + 1e-6f); }
; __device__ __forceinline__ float silu_mul(float a, float b) { return a * b * __builtin_amdgcn_rcpf(1.0f + __builtin_amdgcn_exp2f(-a * LOG2E)); }
;     __device__ __forceinline__ void operator()(const f32x4 (&acc)[2][2][4][2], const Unit& u, int wr, int wc, int fr, int fq) const {
;     ...
;         const float rsl0 = row_rstd(ss, u.pm * BM + wr * 64 + lane), rsl1 = row_rstd(ss, u.pm * BM + HALF + wr * 64 + lane);
; #pragma unroll
;         for (int ai = 0; ai < 2; ++ai)
; #pragma unroll
;             for (int m = 0; m < 4; ++m) { const int row = row0 + ai * HALF + m * 16; const float rs = __shfl(ai ? rsl1 : rsl0, m * 16 + fr); bf16_t* rowp = O + (size_t)row * DFF + col0;
;                 const f32x4 a0 = acc[ai][0][m][0] * rs + ba0, a1 = acc[ai][0][m][1] * rs + ba1, b0 = acc[ai][1][m][0] * rs + bb0, b1 = acc[ai][1][m][1] * rs + bb1;
;                 u32x4 w; w.x = cvt_pk_bf16(silu_mul(a0[0], b0[0]), silu_mul(a0[1], b0[1])); w.y = cvt_pk_bf16(silu_mul(a0[2], b0[2]), silu_mul(a0[3], b0[3]));
;                 w.z = cvt_pk_bf16(silu_mul(a1[0], b1[0]), silu_mul(a1[1], b1[1])); w.w = cvt_pk_bf16(silu_mul(a1[2], b1[2]), silu_mul(a1[3], b1[3]));
;                 *(u32x4*)rowp = w; }
	v_cvt_pk_bf16_f32 v239, v88, v89
	v_pk_mul_f32 v[234:235], v[90:91], s[100:101] op_sel_hi:[1,0]
	v_pk_mul_f32 v[236:237], v[92:93], s[100:101] op_sel_hi:[1,0]
	v_exp_f32_e32 v234, v234
	v_exp_f32_e32 v235, v235
	v_exp_f32_e32 v236, v236
	v_exp_f32_e32 v237, v237
	v_pk_add_f32 v[234:235], v[234:235], 1.0 op_sel_hi:[1,0]
	v_pk_add_f32 v[236:237], v[236:237], 1.0 op_sel_hi:[1,0]
	v_rcp_f32_e32 v234, v234
	v_rcp_f32_e32 v235, v235
	v_rcp_f32_e32 v236, v236
	v_rcp_f32_e32 v237, v237
	v_pk_mul_f32 v[82:83], v[90:91], v[82:83]
	v_pk_mul_f32 v[84:85], v[92:93], v[84:85]
	v_pk_mul_f32 v[82:83], v[82:83], v[234:235]
	v_pk_mul_f32 v[84:85], v[84:85], v[236:237]
	v_cvt_pk_bf16_f32 v240, v82, v83
	v_cvt_pk_bf16_f32 v241, v84, v85
	global_store_dwordx4 v[100:101], v[238:241], off
	s_nop 1
	v_div_scale_f32 v82, s[2:3], v182, v182, 1.0
	v_rcp_f32_e32 v84, v82
	v_add_u32_e32 v83, 0x80, v181
	v_fma_f32 v85, -v82, v84, 1.0
	v_fmac_f32_e32 v84, v85, v84
	v_div_scale_f32 v85, vcc, 1.0, v182, 1.0
	v_mul_f32_e32 v86, v85, v84
	v_fma_f32 v87, -v82, v86, v85
	v_fmac_f32_e32 v86, v87, v84
	v_fma_f32 v82, -v82, v86, v85
	v_div_fmas_f32 v82, v82, v84, v86
	v_div_fixup_f32 v82, v82, v182, 1.0
	ds_bpermute_b32 v242, v180, v82
	ds_bpermute_b32 v244, v180, v82 offset:64
	ds_bpermute_b32 v246, v180, v82 offset:128
	ds_bpermute_b32 v248, v180, v82 offset:192
	v_mad_i64_i32 v[86:87], s[2:3], v83, s59, v[162:163]
	v_lshl_add_u64 v[86:87], v[86:87], 0, v[164:165]
	s_andn2_b64 vcc, exec, s[38:39]
	s_waitcnt lgkmcnt(0)
	v_pk_fma_f32 v[62:63], v[62:63], v[242:243], v[78:79] op_sel_hi:[1,0,1]
	v_pk_fma_f32 v[64:65], v[64:65], v[242:243], v[80:81] op_sel_hi:[1,0,1]
	v_pk_fma_f32 v[54:55], v[54:55], v[242:243], v[70:71] op_sel_hi:[1,0,1]
	v_pk_fma_f32 v[56:57], v[56:57], v[242:243], v[72:73] op_sel_hi:[1,0,1]
	v_pk_fma_f32 v[58:59], v[58:59], v[242:243], v[74:75] op_sel_hi:[1,0,1]
	v_pk_fma_f32 v[60:61], v[60:61], v[242:243], v[76:77] op_sel_hi:[1,0,1]
	v_pk_fma_f32 v[50:51], v[50:51], v[242:243], v[66:67] op_sel_hi:[1,0,1]
	v_pk_fma_f32 v[52:53], v[52:53], v[242:243], v[68:69] op_sel_hi:[1,0,1]
	v_pk_mul_f32 v[234:235], v[62:63], s[100:101] op_sel_hi:[1,0]
	v_pk_mul_f32 v[236:237], v[64:65], s[100:101] op_sel_hi:[1,0]
	v_exp_f32_e32 v234, v234
	v_exp_f32_e32 v235, v235
	v_exp_f32_e32 v236, v236
	v_exp_f32_e32 v237, v237
	v_pk_add_f32 v[234:235], v[234:235], 1.0 op_sel_hi:[1,0]
	v_pk_add_f32 v[236:237], v[236:237], 1.0 op_sel_hi:[1,0]
	v_rcp_f32_e32 v234, v234
	v_rcp_f32_e32 v235, v235
	v_rcp_f32_e32 v236, v236
	v_rcp_f32_e32 v237, v237
	v_pk_mul_f32 v[54:55], v[62:63], v[54:55]
	v_pk_mul_f32 v[56:57], v[64:65], v[56:57]
	v_pk_mul_f32 v[54:55], v[54:55], v[234:235]
	v_pk_mul_f32 v[56:57], v[56:57], v[236:237]
	v_cvt_pk_bf16_f32 v238, v54, v55
	v_cvt_pk_bf16_f32 v239, v56, v57
	v_pk_mul_f32 v[234:235], v[58:59], s[100:101] op_sel_hi:[1,0]
	v_pk_mul_f32 v[236:237], v[60:61], s[100:101] op_sel_hi:[1,0]
	v_exp_f32_e32 v234, v234
	v_exp_f32_e32 v235, v235
	v_exp_f32_e32 v236, v236
	v_exp_f32_e32 v237, v237
	v_pk_add_f32 v[234:235], v[234:235], 1.0 op_sel_hi:[1,0]
	v_pk_add_f32 v[236:237], v[236:237], 1.0 op_sel_hi:[1,0]
	v_rcp_f32_e32 v234, v234
	v_rcp_f32_e32 v235, v235
	v_rcp_f32_e32 v236, v236
	v_rcp_f32_e32 v237, v237
	v_pk_mul_f32 v[50:51], v[58:59], v[50:51]
	v_pk_mul_f32 v[52:53], v[60:61], v[52:53]
	v_pk_mul_f32 v[50:51], v[50:51], v[234:235]
	v_pk_mul_f32 v[52:53], v[52:53], v[236:237]
	v_cvt_pk_bf16_f32 v240, v50, v51
	v_cvt_pk_bf16_f32 v241, v52, v53
	global_store_dwordx4 v[86:87], v[238:241], off
	v_add_u32_e32 v51, 0x90, v181
	v_mad_i64_i32 v[52:53], s[2:3], v51, s59, v[162:163]
	v_lshl_add_u64 v[52:53], v[52:53], 0, v[164:165]
	v_pk_fma_f32 v[46:47], v[46:47], v[244:245], v[78:79] op_sel_hi:[1,0,1]
	v_pk_fma_f32 v[48:49], v[48:49], v[244:245], v[80:81] op_sel_hi:[1,0,1]
	v_pk_fma_f32 v[38:39], v[38:39], v[244:245], v[70:71] op_sel_hi:[1,0,1]
	v_pk_fma_f32 v[40:41], v[40:41], v[244:245], v[72:73] op_sel_hi:[1,0,1]
	v_pk_fma_f32 v[42:43], v[42:43], v[244:245], v[74:75] op_sel_hi:[1,0,1]
	v_pk_fma_f32 v[44:45], v[44:45], v[244:245], v[76:77] op_sel_hi:[1,0,1]
	v_pk_fma_f32 v[34:35], v[34:35], v[244:245], v[66:67] op_sel_hi:[1,0,1]
	v_pk_fma_f32 v[36:37], v[36:37], v[244:245], v[68:69] op_sel_hi:[1,0,1]
	v_pk_mul_f32 v[234:235], v[46:47], s[100:101] op_sel_hi:[1,0]
	v_pk_mul_f32 v[236:237], v[48:49], s[100:101] op_sel_hi:[1,0]
	v_exp_f32_e32 v234, v234
	v_exp_f32_e32 v235, v235
	v_exp_f32_e32 v236, v236
	v_exp_f32_e32 v237, v237
	v_pk_add_f32 v[234:235], v[234:235], 1.0 op_sel_hi:[1,0]
	v_pk_add_f32 v[236:237], v[236:237], 1.0 op_sel_hi:[1,0]
	v_rcp_f32_e32 v234, v234
	v_rcp_f32_e32 v235, v235
	v_rcp_f32_e32 v236, v236
	v_rcp_f32_e32 v237, v237
	v_pk_mul_f32 v[38:39], v[46:47], v[38:39]
	v_pk_mul_f32 v[40:41], v[48:49], v[40:41]
	v_pk_mul_f32 v[38:39], v[38:39], v[234:235]
	v_pk_mul_f32 v[40:41], v[40:41], v[236:237]
	v_cvt_pk_bf16_f32 v238, v38, v39
	v_cvt_pk_bf16_f32 v239, v40, v41
	v_pk_mul_f32 v[234:235], v[42:43], s[100:101] op_sel_hi:[1,0]
	v_pk_mul_f32 v[236:237], v[44:45], s[100:101] op_sel_hi:[1,0]
; __device__ __forceinline__ unsigned cvt_pk_bf16(float lo, float hi) { unsigned r; asm volatile("v_cvt_pk_bf16_f32 %0, %1, %2" : "=v"(r) : "v"(lo), "v"(hi)); return r; }
; __device__ __forceinline__ float silu_mul(float a, float b) { return a * b * __builtin_amdgcn_rcpf(1.0f + __builtin_amdgcn_exp2f(-a * LOG2E)); }
; #define PG8_BAR __builtin_amdgcn_s_barrier()
;     __device__ __forceinline__ void operator()(const f32x4 (&acc)[2][2][4][2], const Unit& u, int wr, int wc, int fr, int fq) const {
;     ...
;             for (int m = 0; m < 4; ++m) { const int row = row0 + ai * HALF + m * 16; const float rs = __shfl(ai ? rsl1 : rsl0, m * 16 + fr); bf16_t* rowp = O + (size_t)row * DFF + col0;
;                 const f32x4 a0 = acc[ai][0][m][0] * rs + ba0, a1 = acc[ai][0][m][1] * rs + ba1, b0 = acc[ai][1][m][0] * rs + bb0, b1 = acc[ai][1][m][1] * rs + bb1;
;                 u32x4 w; w.x = cvt_pk_bf16(silu_mul(a0[0], b0[0]), silu_mul(a0[1], b0[1])); w.y = cvt_pk_bf16(silu_mul(a0[2], b0[2]), silu_mul(a0[3], b0[3]));
;                 w.z = cvt_pk_bf16(silu_mul(a1[0], b1[0]), silu_mul(a1[1], b1[1])); w.w = cvt_pk_bf16(silu_mul(a1[2], b1[2]), silu_mul(a1[3], b1[3]));
;                 *(u32x4*)rowp = w; }
; template <class Epi, class Sched, bool ALIGN_EPI = false, bool SP2 = false>
; __device__ __forceinline__ void gemm_phase(LAS unsigned char* lds, const Gemm g, const Sched& S, const Epi& E) {
;     ...
;         if (!has_next) break;
; #pragma unroll
;         for (int a = 0; a < 2; ++a)
; #pragma unroll
;             for (int b = 0; b < 2; ++b)
; #pragma unroll
;                 for (int m = 0; m < 4; ++m)
; #pragma unroll
;                     for (int n = 0; n < 2; ++n) acc[a][b][m][n] = (f32x4){0.f, 0.f, 0.f, 0.f};
;         cur = nxt; cA = nA; cB = nB; ++ui;
;         if constexpr (ALIGN_EPI) { if (wr == 1) PG8_BAR; }
	v_exp_f32_e32 v234, v234
	v_exp_f32_e32 v235, v235
	v_exp_f32_e32 v236, v236
	v_exp_f32_e32 v237, v237
	v_pk_add_f32 v[234:235], v[234:235], 1.0 op_sel_hi:[1,0]
	v_pk_add_f32 v[236:237], v[236:237], 1.0 op_sel_hi:[1,0]
	v_rcp_f32_e32 v234, v234
	v_rcp_f32_e32 v235, v235
	v_rcp_f32_e32 v236, v236
	v_rcp_f32_e32 v237, v237
	v_pk_mul_f32 v[34:35], v[42:43], v[34:35]
	v_pk_mul_f32 v[36:37], v[44:45], v[36:37]
	v_pk_mul_f32 v[34:35], v[34:35], v[234:235]
	v_pk_mul_f32 v[36:37], v[36:37], v[236:237]
	v_cvt_pk_bf16_f32 v240, v34, v35
	v_cvt_pk_bf16_f32 v241, v36, v37
	global_store_dwordx4 v[52:53], v[238:241], off
	v_add_u32_e32 v35, 0xa0, v181
	v_mad_i64_i32 v[36:37], s[2:3], v35, s59, v[162:163]
	v_lshl_add_u64 v[36:37], v[36:37], 0, v[164:165]
	v_pk_fma_f32 v[30:31], v[30:31], v[246:247], v[78:79] op_sel_hi:[1,0,1]
	v_pk_fma_f32 v[32:33], v[32:33], v[246:247], v[80:81] op_sel_hi:[1,0,1]
	v_pk_fma_f32 v[22:23], v[22:23], v[246:247], v[70:71] op_sel_hi:[1,0,1]
	v_pk_fma_f32 v[24:25], v[24:25], v[246:247], v[72:73] op_sel_hi:[1,0,1]
	v_pk_fma_f32 v[26:27], v[26:27], v[246:247], v[74:75] op_sel_hi:[1,0,1]
	v_pk_fma_f32 v[28:29], v[28:29], v[246:247], v[76:77] op_sel_hi:[1,0,1]
	v_pk_fma_f32 v[18:19], v[18:19], v[246:247], v[66:67] op_sel_hi:[1,0,1]
	v_pk_fma_f32 v[20:21], v[20:21], v[246:247], v[68:69] op_sel_hi:[1,0,1]
	v_pk_mul_f32 v[234:235], v[30:31], s[100:101] op_sel_hi:[1,0]
	v_pk_mul_f32 v[236:237], v[32:33], s[100:101] op_sel_hi:[1,0]
	v_exp_f32_e32 v234, v234
	v_exp_f32_e32 v235, v235
	v_exp_f32_e32 v236, v236
	v_exp_f32_e32 v237, v237
	v_pk_add_f32 v[234:235], v[234:235], 1.0 op_sel_hi:[1,0]
	v_pk_add_f32 v[236:237], v[236:237], 1.0 op_sel_hi:[1,0]
	v_rcp_f32_e32 v234, v234
	v_rcp_f32_e32 v235, v235
	v_rcp_f32_e32 v236, v236
	v_rcp_f32_e32 v237, v237
	v_pk_mul_f32 v[22:23], v[30:31], v[22:23]
	v_pk_mul_f32 v[24:25], v[32:33], v[24:25]
	v_pk_mul_f32 v[22:23], v[22:23], v[234:235]
	v_pk_mul_f32 v[24:25], v[24:25], v[236:237]
	v_cvt_pk_bf16_f32 v238, v22, v23
	v_cvt_pk_bf16_f32 v239, v24, v25
	v_pk_mul_f32 v[234:235], v[26:27], s[100:101] op_sel_hi:[1,0]
	v_pk_mul_f32 v[236:237], v[28:29], s[100:101] op_sel_hi:[1,0]
	v_exp_f32_e32 v234, v234
	v_exp_f32_e32 v235, v235
	v_exp_f32_e32 v236, v236
	v_exp_f32_e32 v237, v237
	v_pk_add_f32 v[234:235], v[234:235], 1.0 op_sel_hi:[1,0]
	v_pk_add_f32 v[236:237], v[236:237], 1.0 op_sel_hi:[1,0]
	v_rcp_f32_e32 v234, v234
	v_rcp_f32_e32 v235, v235
	v_rcp_f32_e32 v236, v236
	v_rcp_f32_e32 v237, v237
	v_pk_mul_f32 v[18:19], v[26:27], v[18:19]
	v_pk_mul_f32 v[20:21], v[28:29], v[20:21]
	v_pk_mul_f32 v[18:19], v[18:19], v[234:235]
	v_pk_mul_f32 v[20:21], v[20:21], v[236:237]
	v_cvt_pk_bf16_f32 v240, v18, v19
	v_cvt_pk_bf16_f32 v241, v20, v21
	global_store_dwordx4 v[36:37], v[238:241], off
	v_add_u32_e32 v19, 0xb0, v181
	v_mad_i64_i32 v[20:21], s[2:3], v19, s59, v[162:163]
	v_lshl_add_u64 v[20:21], v[20:21], 0, v[164:165]
	s_mov_b64 s[2:3], -1
	v_pk_fma_f32 v[14:15], v[14:15], v[248:249], v[78:79] op_sel_hi:[1,0,1]
	v_pk_fma_f32 v[16:17], v[16:17], v[248:249], v[80:81] op_sel_hi:[1,0,1]
	v_pk_fma_f32 v[6:7], v[6:7], v[248:249], v[70:71] op_sel_hi:[1,0,1]
	v_pk_fma_f32 v[8:9], v[8:9], v[248:249], v[72:73] op_sel_hi:[1,0,1]
	v_pk_fma_f32 v[10:11], v[10:11], v[248:249], v[74:75] op_sel_hi:[1,0,1]
	v_pk_fma_f32 v[12:13], v[12:13], v[248:249], v[76:77] op_sel_hi:[1,0,1]
	v_pk_fma_f32 v[2:3], v[2:3], v[248:249], v[66:67] op_sel_hi:[1,0,1]
	v_pk_fma_f32 v[4:5], v[4:5], v[248:249], v[68:69] op_sel_hi:[1,0,1]
	v_pk_mul_f32 v[234:235], v[14:15], s[100:101] op_sel_hi:[1,0]
	v_pk_mul_f32 v[236:237], v[16:17], s[100:101] op_sel_hi:[1,0]
	v_exp_f32_e32 v234, v234
	v_exp_f32_e32 v235, v235
	v_exp_f32_e32 v236, v236
	v_exp_f32_e32 v237, v237
	v_pk_add_f32 v[234:235], v[234:235], 1.0 op_sel_hi:[1,0]
	v_pk_add_f32 v[236:237], v[236:237], 1.0 op_sel_hi:[1,0]
	v_rcp_f32_e32 v234, v234
	v_rcp_f32_e32 v235, v235
	v_rcp_f32_e32 v236, v236
	v_rcp_f32_e32 v237, v237
	v_pk_mul_f32 v[6:7], v[14:15], v[6:7]
	v_pk_mul_f32 v[8:9], v[16:17], v[8:9]
	v_pk_mul_f32 v[6:7], v[6:7], v[234:235]
	v_pk_mul_f32 v[8:9], v[8:9], v[236:237]
	v_cvt_pk_bf16_f32 v238, v6, v7
	v_cvt_pk_bf16_f32 v239, v8, v9
	v_pk_mul_f32 v[234:235], v[10:11], s[100:101] op_sel_hi:[1,0]
	v_pk_mul_f32 v[236:237], v[12:13], s[100:101] op_sel_hi:[1,0]
	v_exp_f32_e32 v234, v234
	v_exp_f32_e32 v235, v235
	v_exp_f32_e32 v236, v236
	v_exp_f32_e32 v237, v237
	v_pk_add_f32 v[234:235], v[234:235], 1.0 op_sel_hi:[1,0]
	v_pk_add_f32 v[236:237], v[236:237], 1.0 op_sel_hi:[1,0]
	v_rcp_f32_e32 v234, v234
	v_rcp_f32_e32 v235, v235
	v_rcp_f32_e32 v236, v236
	v_rcp_f32_e32 v237, v237
	v_pk_mul_f32 v[2:3], v[10:11], v[2:3]
	v_pk_mul_f32 v[4:5], v[12:13], v[4:5]
	v_pk_mul_f32 v[2:3], v[2:3], v[234:235]
	v_pk_mul_f32 v[4:5], v[4:5], v[236:237]
	v_cvt_pk_bf16_f32 v240, v2, v3
	v_cvt_pk_bf16_f32 v241, v4, v5
	global_store_dwordx4 v[20:21], v[238:241], off
	s_waitcnt vmcnt(8)
	s_setprio 0
	s_cbranch_vccnz .LBB0_184
	s_andn2_b64 vcc, exec, s[4:5]
	s_cbranch_vccnz .LBB0_183
	s_barrier
	s_branch .LBB0_183

; __device__ __forceinline__ unsigned cvt_pk_bf16(float lo, float hi) { unsigned r; asm volatile("v_cvt_pk_bf16_f32 %0, %1, %2" : "=v"(r) : "v"(lo), "v"(hi)); return r; }
; __device__ __forceinline__ float row_rstd(const float* ss, int row) { return 1.0f / sqrtf(ss[row] * (1.0f / DM) + 1e-6f); }
; __device__ __forceinline__ float silu_mul(float a, float b) { return a * b * __builtin_amdgcn_rcpf(1.0f + __builtin_amdgcn_exp2f(-a * LOG2E)); }
; #define PG8_BAR __builtin_amdgcn_s_barrier()
;     __device__ __forceinline__ void operator()(const f32x4 (&acc)[2][2][4][2], const Unit& u, int wr, int wc, int fr, int fq) const {
;         const int row0 = u.pm * BM + wr * 64 + fr, col0 = u.pn * HALF + wc * 32 + 8 * fq;
;         const int s = (u.pm < ML / BM) ? (u.pm >> 5) : 4;
;         const float* bp = bias + (size_t)s * BIAS_N + u.pn * BM + wc * 32 + 8 * fq;
;         const f32x4 ba0 = *(const f32x4*)bp, ba1 = *(const f32x4*)(bp + 4), bb0 = *(const f32x4*)(bp + HALF), bb1 = *(const f32x4*)(bp + HALF + 4);
;         const int lane = fq * 16 + fr;
;         const float rsl0 = row_rstd(ss, u.pm * BM + wr * 64 + lane), rsl1 = row_rstd(ss, u.pm * BM + HALF + wr * 64 + lane);
; #pragma unroll
;         for (int ai = 0; ai < 2; ++ai)
; #pragma unroll
;             for (int m = 0; m < 4; ++m) { const int row = row0 + ai * HALF + m * 16; const float rs = __shfl(ai ? rsl1 : rsl0, m * 16 + fr); bf16_t* rowp = O + (size_t)row * DFF + col0;
;                 const f32x4 a0 = acc[ai][0][m][0] * rs + ba0, a1 = acc[ai][0][m][1] * rs + ba1, b0 = acc[ai][1][m][0] * rs + bb0, b1 = acc[ai][1][m][1] * rs + bb1;
;                 u32x4 w; w.x = cvt_pk_bf16(silu_mul(a0[0], b0[0]), silu_mul(a0[1], b0[1])); w.y = cvt_pk_bf16(silu_mul(a0[2], b0[2]), silu_mul(a0[3], b0[3]));
;                 w.z = cvt_pk_bf16(silu_mul(a1[0], b1[0]), silu_mul(a1[1], b1[1])); w.w = cvt_pk_bf16(silu_mul(a1[2], b1[2]), silu_mul(a1[3], b1[3]));
;                 *(u32x4*)rowp = w; }
; template <class Epi, class Sched, bool ALIGN_EPI = false, bool SP2 = false>
; __device__ __forceinline__ void gemm_phase(LAS unsigned char* lds, const Gemm g, const Sched& S, const Epi& E) {
;     ...
;         if constexpr (ALIGN_EPI) { if (wr == 0) PG8_BAR; }
;         if constexpr (!Epi::AFTER_DRAIN) { E(acc, cur, wr, wc, fr, fq); S.done(cur); }
.LBB0_1470:
	s_lshl_b32 s2, s2, 8
	s_add_i32 s13, s2, s42
	s_lshl_b64 s[2:3], s[16:17], 2
	s_add_u32 s15, s43, s2
	s_addc_u32 s16, s44, s3
	s_lshl_b32 s2, s0, 8
	s_ashr_i32 s3, s2, 31
	s_lshl_b64 s[2:3], s[2:3], 2
	v_lshl_or_b32 v164, s0, 7, v173
	s_add_u32 s0, s15, s2
	s_addc_u32 s3, s16, s3
	v_or_b32_e32 v162, s13, v171
	s_add_u32 s2, s0, s50
	v_ashrrev_i32_e32 v163, 31, v162
	s_addc_u32 s3, s3, 0
	v_lshl_add_u64 v[162:163], v[162:163], 2, s[64:65]
	v_mov_b32_e32 v74, v234
	v_mov_b32_e32 v75, v235
	v_mov_b32_e32 v76, v236
	v_mov_b32_e32 v77, v237
	v_mov_b32_e32 v78, v238
	v_mov_b32_e32 v79, v239
	v_mov_b32_e32 v80, v240
	v_mov_b32_e32 v81, v241
	v_mov_b32_e32 v66, v242
	v_mov_b32_e32 v67, v243
	v_mov_b32_e32 v68, v244
	v_mov_b32_e32 v69, v245
	v_mov_b32_e32 v70, v246
	v_mov_b32_e32 v71, v247
	v_mov_b32_e32 v72, v248
	v_mov_b32_e32 v73, v249
	v_or_b32_e32 v181, s13, v169
	v_mov_b32_e32 v162, v250
	v_fmamk_f32 v162, v162, 0x3a000000, v178
	v_cmp_gt_f32_e32 vcc, s51, v162
	v_mul_f32_e32 v163, 0x4f800000, v162
	s_nop 0
	v_cndmask_b32_e32 v162, v162, v163, vcc
	v_sqrt_f32_e32 v163, v162
	s_nop 0
	v_add_u32_e32 v165, -1, v163
	v_fma_f32 v166, -v165, v163, v162
	v_cmp_ge_f32_e64 s[2:3], 0, v166
	v_add_u32_e32 v166, 1, v163
	s_nop 0
	v_cndmask_b32_e64 v165, v163, v165, s[2:3]
	v_fma_f32 v163, -v166, v163, v162
	v_cmp_lt_f32_e64 s[2:3], 0, v163
	s_nop 1
	v_cndmask_b32_e64 v163, v165, v166, s[2:3]
	v_mul_f32_e32 v165, 0x37800000, v163
	v_cndmask_b32_e32 v163, v163, v165, vcc
	v_cmp_class_f32_e32 vcc, v162, v179
	s_nop 1
	v_cndmask_b32_e32 v166, v163, v162, vcc
	v_add_u32_e32 v162, s13, v172
	v_ashrrev_i32_e32 v163, 31, v162
	v_lshl_add_u64 v[162:163], v[162:163], 2, s[64:65]
	v_mov_b32_e32 v162, v251
	v_fmamk_f32 v162, v162, 0x3a000000, v178
	v_cmp_gt_f32_e32 vcc, s51, v162
	v_mul_f32_e32 v163, 0x4f800000, v162
	s_nop 0
	v_cndmask_b32_e32 v162, v162, v163, vcc
	v_sqrt_f32_e32 v163, v162
	s_nop 0
	v_add_u32_e32 v165, -1, v163
	v_fma_f32 v167, -v165, v163, v162
	v_cmp_ge_f32_e64 s[2:3], 0, v167
	v_add_u32_e32 v167, 1, v163
	s_nop 0
	v_cndmask_b32_e64 v165, v163, v165, s[2:3]
	v_fma_f32 v163, -v167, v163, v162
	v_cmp_lt_f32_e64 s[2:3], 0, v163
	s_nop 1
	v_cndmask_b32_e64 v163, v165, v167, s[2:3]
	v_mul_f32_e32 v165, 0x37800000, v163
	v_cndmask_b32_e32 v163, v163, v165, vcc
	v_cmp_class_f32_e32 vcc, v162, v179
	v_ashrrev_i32_e32 v165, 31, v164
	v_lshlrev_b64 v[164:165], 1, v[164:165]
	v_cndmask_b32_e32 v182, v163, v162, vcc
	v_div_scale_f32 v162, s[2:3], v166, v166, 1.0
	v_rcp_f32_e32 v163, v162
	s_nop 0
	v_fma_f32 v167, -v162, v163, 1.0
	v_fmac_f32_e32 v163, v167, v163
	v_div_scale_f32 v167, vcc, 1.0, v166, 1.0
	v_mul_f32_e32 v168, v167, v163
	v_fma_f32 v183, -v162, v168, v167
	v_fmac_f32_e32 v168, v183, v163
	v_fma_f32 v162, -v162, v168, v167
	v_div_fmas_f32 v162, v162, v163, v168
	v_div_fixup_f32 v183, v162, v166, 1.0
	s_and_b64 vcc, exec, s[10:11]
	s_cbranch_vccz .Lalign_1468
	s_barrier
	s_setprio 1
.Lalign_1468:
	s_mov_b32 s100, 0xbfb8aa3b
	ds_bpermute_b32 v242, v180, v183
	ds_bpermute_b32 v244, v180, v183 offset:64
	ds_bpermute_b32 v246, v180, v183 offset:128
	ds_bpermute_b32 v248, v180, v183 offset:192
	v_mov_b64_e32 v[162:163], s[96:97]
	v_mad_i64_i32 v[166:167], s[2:3], v181, s49, v[162:163]
	v_lshl_add_u64 v[166:167], v[166:167], 0, v[164:165]
	s_waitcnt lgkmcnt(0)
	v_pk_fma_f32 v[142:143], v[142:143], v[242:243], v[78:79] op_sel_hi:[1,0,1]
	v_pk_fma_f32 v[144:145], v[144:145], v[242:243], v[80:81] op_sel_hi:[1,0,1]
	v_pk_fma_f32 v[134:135], v[134:135], v[242:243], v[70:71] op_sel_hi:[1,0,1]
	v_pk_fma_f32 v[136:137], v[136:137], v[242:243], v[72:73] op_sel_hi:[1,0,1]
	v_pk_fma_f32 v[138:139], v[138:139], v[242:243], v[74:75] op_sel_hi:[1,0,1]
	v_pk_fma_f32 v[140:141], v[140:141], v[242:243], v[76:77] op_sel_hi:[1,0,1]
	v_pk_fma_f32 v[130:131], v[130:131], v[242:243], v[66:67] op_sel_hi:[1,0,1]
	v_pk_fma_f32 v[132:133], v[132:133], v[242:243], v[68:69] op_sel_hi:[1,0,1]
	v_pk_mul_f32 v[234:235], v[142:143], s[100:101] op_sel_hi:[1,0]
	v_pk_mul_f32 v[236:237], v[144:145], s[100:101] op_sel_hi:[1,0]
	v_exp_f32_e32 v234, v234
	v_exp_f32_e32 v235, v235
	v_exp_f32_e32 v236, v236
	v_exp_f32_e32 v237, v237
	v_pk_add_f32 v[234:235], v[234:235], 1.0 op_sel_hi:[1,0]
	v_pk_add_f32 v[236:237], v[236:237], 1.0 op_sel_hi:[1,0]
	v_rcp_f32_e32 v234, v234
	v_rcp_f32_e32 v235, v235
	v_rcp_f32_e32 v236, v236
	v_rcp_f32_e32 v237, v237
	v_pk_mul_f32 v[134:135], v[142:143], v[134:135]
	v_pk_mul_f32 v[136:137], v[144:145], v[136:137]
	v_pk_mul_f32 v[134:135], v[134:135], v[234:235]
	v_pk_mul_f32 v[136:137], v[136:137], v[236:237]
	v_cvt_pk_bf16_f32 v238, v134, v135
	v_cvt_pk_bf16_f32 v239, v136, v137
	v_pk_mul_f32 v[234:235], v[138:139], s[100:101] op_sel_hi:[1,0]
	v_pk_mul_f32 v[236:237], v[140:141], s[100:101] op_sel_hi:[1,0]
	v_exp_f32_e32 v234, v234
	v_exp_f32_e32 v235, v235
	v_exp_f32_e32 v236, v236
	v_exp_f32_e32 v237, v237
	v_pk_add_f32 v[234:235], v[234:235], 1.0 op_sel_hi:[1,0]
	v_pk_add_f32 v[236:237], v[236:237], 1.0 op_sel_hi:[1,0]
	v_rcp_f32_e32 v234, v234
	v_rcp_f32_e32 v235, v235
	v_rcp_f32_e32 v236, v236
	v_rcp_f32_e32 v237, v237
	v_pk_mul_f32 v[130:131], v[138:139], v[130:131]
	v_pk_mul_f32 v[132:133], v[140:141], v[132:133]
	v_pk_mul_f32 v[130:131], v[130:131], v[234:235]
	v_pk_mul_f32 v[132:133], v[132:133], v[236:237]
	v_cvt_pk_bf16_f32 v240, v130, v131
	v_cvt_pk_bf16_f32 v241, v132, v133
	global_store_dwordx4 v[166:167], v[238:241], off
	v_or_b32_e32 v131, 16, v181
	v_mad_i64_i32 v[132:133], s[2:3], v131, s49, v[162:163]
	v_lshl_add_u64 v[132:133], v[132:133], 0, v[164:165]
	v_pk_fma_f32 v[126:127], v[126:127], v[244:245], v[78:79] op_sel_hi:[1,0,1]
; __device__ __forceinline__ unsigned cvt_pk_bf16(float lo, float hi) { unsigned r; asm volatile("v_cvt_pk_bf16_f32 %0, %1, %2" : "=v"(r) : "v"(lo), "v"(hi)); return r; }
; __device__ __forceinline__ float silu_mul(float a, float b) { return a * b * __builtin_amdgcn_rcpf(1.0f + __builtin_amdgcn_exp2f(-a * LOG2E)); }
;     __device__ __forceinline__ void operator()(const f32x4 (&acc)[2][2][4][2], const Unit& u, int wr, int wc, int fr, int fq) const {
;     ...
;             for (int m = 0; m < 4; ++m) { const int row = row0 + ai * HALF + m * 16; const float rs = __shfl(ai ? rsl1 : rsl0, m * 16 + fr); bf16_t* rowp = O + (size_t)row * DFF + col0;
;                 const f32x4 a0 = acc[ai][0][m][0] * rs + ba0, a1 = acc[ai][0][m][1] * rs + ba1, b0 = acc[ai][1][m][0] * rs + bb0, b1 = acc[ai][1][m][1] * rs + bb1;
;                 u32x4 w; w.x = cvt_pk_bf16(silu_mul(a0[0], b0[0]), silu_mul(a0[1], b0[1])); w.y = cvt_pk_bf16(silu_mul(a0[2], b0[2]), silu_mul(a0[3], b0[3]));
;                 w.z = cvt_pk_bf16(silu_mul(a1[0], b1[0]), silu_mul(a1[1], b1[1])); w.w = cvt_pk_bf16(silu_mul(a1[2], b1[2]), silu_mul(a1[3], b1[3]));
;                 *(u32x4*)rowp = w; }
	v_pk_fma_f32 v[128:129], v[128:129], v[244:245], v[80:81] op_sel_hi:[1,0,1]
	v_pk_fma_f32 v[118:119], v[118:119], v[244:245], v[70:71] op_sel_hi:[1,0,1]
	v_pk_fma_f32 v[120:121], v[120:121], v[244:245], v[72:73] op_sel_hi:[1,0,1]
	v_pk_fma_f32 v[122:123], v[122:123], v[244:245], v[74:75] op_sel_hi:[1,0,1]
	v_pk_fma_f32 v[124:125], v[124:125], v[244:245], v[76:77] op_sel_hi:[1,0,1]
	v_pk_fma_f32 v[114:115], v[114:115], v[244:245], v[66:67] op_sel_hi:[1,0,1]
	v_pk_fma_f32 v[116:117], v[116:117], v[244:245], v[68:69] op_sel_hi:[1,0,1]
	v_pk_mul_f32 v[234:235], v[126:127], s[100:101] op_sel_hi:[1,0]
	v_pk_mul_f32 v[236:237], v[128:129], s[100:101] op_sel_hi:[1,0]
	v_exp_f32_e32 v234, v234
	v_exp_f32_e32 v235, v235
	v_exp_f32_e32 v236, v236
	v_exp_f32_e32 v237, v237
	v_pk_add_f32 v[234:235], v[234:235], 1.0 op_sel_hi:[1,0]
	v_pk_add_f32 v[236:237], v[236:237], 1.0 op_sel_hi:[1,0]
	v_rcp_f32_e32 v234, v234
	v_rcp_f32_e32 v235, v235
	v_rcp_f32_e32 v236, v236
	v_rcp_f32_e32 v237, v237
	v_pk_mul_f32 v[118:119], v[126:127], v[118:119]
	v_pk_mul_f32 v[120:121], v[128:129], v[120:121]
	v_pk_mul_f32 v[118:119], v[118:119], v[234:235]
	v_pk_mul_f32 v[120:121], v[120:121], v[236:237]
	v_cvt_pk_bf16_f32 v238, v118, v119
	v_cvt_pk_bf16_f32 v239, v120, v121
	v_pk_mul_f32 v[234:235], v[122:123], s[100:101] op_sel_hi:[1,0]
	v_pk_mul_f32 v[236:237], v[124:125], s[100:101] op_sel_hi:[1,0]
	v_exp_f32_e32 v234, v234
	v_exp_f32_e32 v235, v235
	v_exp_f32_e32 v236, v236
	v_exp_f32_e32 v237, v237
	v_pk_add_f32 v[234:235], v[234:235], 1.0 op_sel_hi:[1,0]
	v_pk_add_f32 v[236:237], v[236:237], 1.0 op_sel_hi:[1,0]
	v_rcp_f32_e32 v234, v234
	v_rcp_f32_e32 v235, v235
	v_rcp_f32_e32 v236, v236
	v_rcp_f32_e32 v237, v237
	v_pk_mul_f32 v[114:115], v[122:123], v[114:115]
	v_pk_mul_f32 v[116:117], v[124:125], v[116:117]
	v_pk_mul_f32 v[114:115], v[114:115], v[234:235]
	v_pk_mul_f32 v[116:117], v[116:117], v[236:237]
	v_cvt_pk_bf16_f32 v240, v114, v115
	v_cvt_pk_bf16_f32 v241, v116, v117
	global_store_dwordx4 v[132:133], v[238:241], off
	v_or_b32_e32 v115, 32, v181
	v_mad_i64_i32 v[116:117], s[2:3], v115, s49, v[162:163]
	v_lshl_add_u64 v[116:117], v[116:117], 0, v[164:165]
	v_pk_fma_f32 v[110:111], v[110:111], v[246:247], v[78:79] op_sel_hi:[1,0,1]
	v_pk_fma_f32 v[112:113], v[112:113], v[246:247], v[80:81] op_sel_hi:[1,0,1]
	v_pk_fma_f32 v[102:103], v[102:103], v[246:247], v[70:71] op_sel_hi:[1,0,1]
	v_pk_fma_f32 v[104:105], v[104:105], v[246:247], v[72:73] op_sel_hi:[1,0,1]
	v_pk_fma_f32 v[106:107], v[106:107], v[246:247], v[74:75] op_sel_hi:[1,0,1]
	v_pk_fma_f32 v[108:109], v[108:109], v[246:247], v[76:77] op_sel_hi:[1,0,1]
	v_pk_fma_f32 v[98:99], v[98:99], v[246:247], v[66:67] op_sel_hi:[1,0,1]
	v_pk_fma_f32 v[100:101], v[100:101], v[246:247], v[68:69] op_sel_hi:[1,0,1]
	v_pk_mul_f32 v[234:235], v[110:111], s[100:101] op_sel_hi:[1,0]
	v_pk_mul_f32 v[236:237], v[112:113], s[100:101] op_sel_hi:[1,0]
	v_exp_f32_e32 v234, v234
	v_exp_f32_e32 v235, v235
	v_exp_f32_e32 v236, v236
	v_exp_f32_e32 v237, v237
	v_pk_add_f32 v[234:235], v[234:235], 1.0 op_sel_hi:[1,0]
	v_pk_add_f32 v[236:237], v[236:237], 1.0 op_sel_hi:[1,0]
	v_rcp_f32_e32 v234, v234
	v_rcp_f32_e32 v235, v235
	v_rcp_f32_e32 v236, v236
	v_rcp_f32_e32 v237, v237
	v_pk_mul_f32 v[102:103], v[110:111], v[102:103]
	v_pk_mul_f32 v[104:105], v[112:113], v[104:105]
	v_pk_mul_f32 v[102:103], v[102:103], v[234:235]
	v_pk_mul_f32 v[104:105], v[104:105], v[236:237]
	v_cvt_pk_bf16_f32 v238, v102, v103
	v_cvt_pk_bf16_f32 v239, v104, v105
	v_pk_mul_f32 v[234:235], v[106:107], s[100:101] op_sel_hi:[1,0]
	v_pk_mul_f32 v[236:237], v[108:109], s[100:101] op_sel_hi:[1,0]
	v_exp_f32_e32 v234, v234
	v_exp_f32_e32 v235, v235
	v_exp_f32_e32 v236, v236
	v_exp_f32_e32 v237, v237
	v_pk_add_f32 v[234:235], v[234:235], 1.0 op_sel_hi:[1,0]
	v_pk_add_f32 v[236:237], v[236:237], 1.0 op_sel_hi:[1,0]
	v_rcp_f32_e32 v234, v234
	v_rcp_f32_e32 v235, v235
	v_rcp_f32_e32 v236, v236
	v_rcp_f32_e32 v237, v237
	v_pk_mul_f32 v[98:99], v[106:107], v[98:99]
	v_pk_mul_f32 v[100:101], v[108:109], v[100:101]
	v_pk_mul_f32 v[98:99], v[98:99], v[234:235]
	v_pk_mul_f32 v[100:101], v[100:101], v[236:237]
	v_cvt_pk_bf16_f32 v240, v98, v99
	v_cvt_pk_bf16_f32 v241, v100, v101
	global_store_dwordx4 v[116:117], v[238:241], off
	v_or_b32_e32 v99, 48, v181
	v_mad_i64_i32 v[100:101], s[2:3], v99, s49, v[162:163]
	v_lshl_add_u64 v[100:101], v[100:101], 0, v[164:165]
	v_pk_fma_f32 v[94:95], v[94:95], v[248:249], v[78:79] op_sel_hi:[1,0,1]
	v_pk_fma_f32 v[96:97], v[96:97], v[248:249], v[80:81] op_sel_hi:[1,0,1]
	v_pk_fma_f32 v[86:87], v[86:87], v[248:249], v[70:71] op_sel_hi:[1,0,1]
	v_pk_fma_f32 v[88:89], v[88:89], v[248:249], v[72:73] op_sel_hi:[1,0,1]
	v_pk_fma_f32 v[90:91], v[90:91], v[248:249], v[74:75] op_sel_hi:[1,0,1]
	v_pk_fma_f32 v[92:93], v[92:93], v[248:249], v[76:77] op_sel_hi:[1,0,1]
	v_pk_fma_f32 v[82:83], v[82:83], v[248:249], v[66:67] op_sel_hi:[1,0,1]
	v_pk_fma_f32 v[84:85], v[84:85], v[248:249], v[68:69] op_sel_hi:[1,0,1]
	v_pk_mul_f32 v[234:235], v[94:95], s[100:101] op_sel_hi:[1,0]
	v_pk_mul_f32 v[236:237], v[96:97], s[100:101] op_sel_hi:[1,0]
	v_exp_f32_e32 v234, v234
	v_exp_f32_e32 v235, v235
	v_exp_f32_e32 v236, v236
	v_exp_f32_e32 v237, v237
	v_pk_add_f32 v[234:235], v[234:235], 1.0 op_sel_hi:[1,0]
	v_pk_add_f32 v[236:237], v[236:237], 1.0 op_sel_hi:[1,0]
	v_rcp_f32_e32 v234, v234
	v_rcp_f32_e32 v235, v235
	v_rcp_f32_e32 v236, v236
	v_rcp_f32_e32 v237, v237
	v_pk_mul_f32 v[86:87], v[94:95], v[86:87]
	v_pk_mul_f32 v[88:89], v[96:97], v[88:89]
	v_pk_mul_f32 v[86:87], v[86:87], v[234:235]
	v_pk_mul_f32 v[88:89], v[88:89], v[236:237]
	v_cvt_pk_bf16_f32 v238, v86, v87
; __device__ __forceinline__ unsigned cvt_pk_bf16(float lo, float hi) { unsigned r; asm volatile("v_cvt_pk_bf16_f32 %0, %1, %2" : "=v"(r) : "v"(lo), "v"(hi)); return r; }
; __device__ __forceinline__ float row_rstd(const float* ss, int row) { return 1.0f / sqrtf(ss[row] * (1.0f / DM) + 1e-6f); }
; __device__ __forceinline__ float silu_mul(float a, float b) { return a * b * __builtin_amdgcn_rcpf(1.0f + __builtin_amdgcn_exp2f(-a * LOG2E)); }
;     __device__ __forceinline__ void operator()(const f32x4 (&acc)[2][2][4][2], const Unit& u, int wr, int wc, int fr, int fq) const {
;     ...
;         const float rsl0 = row_rstd(ss, u.pm * BM + wr * 64 + lane), rsl1 = row_rstd(ss, u.pm * BM + HALF + wr * 64 + lane);
; #pragma unroll
;         for (int ai = 0; ai < 2; ++ai)
; #pragma unroll
;             for (int m = 0; m < 4; ++m) { const int row = row0 + ai * HALF + m * 16; const float rs = __shfl(ai ? rsl1 : rsl0, m * 16 + fr); bf16_t* rowp = O + (size_t)row * DFF + col0;
;                 const f32x4 a0 = acc[ai][0][m][0] * rs + ba0, a1 = acc[ai][0][m][1] * rs + ba1, b0 = acc[ai][1][m][0] * rs + bb0, b1 = acc[ai][1][m][1] * rs + bb1;
;                 u32x4 w; w.x = cvt_pk_bf16(silu_mul(a0[0], b0[0]), silu_mul(a0[1], b0[1])); w.y = cvt_pk_bf16(silu_mul(a0[2], b0[2]), silu_mul(a0[3], b0[3]));
;                 w.z = cvt_pk_bf16(silu_mul(a1[0], b1[0]), silu_mul(a1[1], b1[1])); w.w = cvt_pk_bf16(silu_mul(a1[2], b1[2]), silu_mul(a1[3], b1[3]));
;                 *(u32x4*)rowp = w; }
	v_cvt_pk_bf16_f32 v239, v88, v89
	v_pk_mul_f32 v[234:235], v[90:91], s[100:101] op_sel_hi:[1,0]
	v_pk_mul_f32 v[236:237], v[92:93], s[100:101] op_sel_hi:[1,0]
	v_exp_f32_e32 v234, v234
	v_exp_f32_e32 v235, v235
	v_exp_f32_e32 v236, v236
	v_exp_f32_e32 v237, v237
	v_pk_add_f32 v[234:235], v[234:235], 1.0 op_sel_hi:[1,0]
	v_pk_add_f32 v[236:237], v[236:237], 1.0 op_sel_hi:[1,0]
	v_rcp_f32_e32 v234, v234
	v_rcp_f32_e32 v235, v235
	v_rcp_f32_e32 v236, v236
	v_rcp_f32_e32 v237, v237
	v_pk_mul_f32 v[82:83], v[90:91], v[82:83]
	v_pk_mul_f32 v[84:85], v[92:93], v[84:85]
	v_pk_mul_f32 v[82:83], v[82:83], v[234:235]
	v_pk_mul_f32 v[84:85], v[84:85], v[236:237]
	v_cvt_pk_bf16_f32 v240, v82, v83
	v_cvt_pk_bf16_f32 v241, v84, v85
	global_store_dwordx4 v[100:101], v[238:241], off
	s_nop 1
	v_div_scale_f32 v82, s[2:3], v182, v182, 1.0
	v_rcp_f32_e32 v84, v82
	v_add_u32_e32 v83, 0x80, v181
	v_fma_f32 v85, -v82, v84, 1.0
	v_fmac_f32_e32 v84, v85, v84
	v_div_scale_f32 v85, vcc, 1.0, v182, 1.0
	v_mul_f32_e32 v86, v85, v84
	v_fma_f32 v87, -v82, v86, v85
	v_fmac_f32_e32 v86, v87, v84
	v_fma_f32 v82, -v82, v86, v85
	v_div_fmas_f32 v82, v82, v84, v86
	v_div_fixup_f32 v82, v82, v182, 1.0
	ds_bpermute_b32 v242, v180, v82
	ds_bpermute_b32 v244, v180, v82 offset:64
	ds_bpermute_b32 v246, v180, v82 offset:128
	ds_bpermute_b32 v248, v180, v82 offset:192
	v_mad_i64_i32 v[86:87], s[2:3], v83, s49, v[162:163]
	v_lshl_add_u64 v[86:87], v[86:87], 0, v[164:165]
	s_andn2_b64 vcc, exec, s[38:39]
	s_waitcnt lgkmcnt(0)
	v_pk_fma_f32 v[62:63], v[62:63], v[242:243], v[78:79] op_sel_hi:[1,0,1]
	v_pk_fma_f32 v[64:65], v[64:65], v[242:243], v[80:81] op_sel_hi:[1,0,1]
	v_pk_fma_f32 v[54:55], v[54:55], v[242:243], v[70:71] op_sel_hi:[1,0,1]
	v_pk_fma_f32 v[56:57], v[56:57], v[242:243], v[72:73] op_sel_hi:[1,0,1]
	v_pk_fma_f32 v[58:59], v[58:59], v[242:243], v[74:75] op_sel_hi:[1,0,1]
	v_pk_fma_f32 v[60:61], v[60:61], v[242:243], v[76:77] op_sel_hi:[1,0,1]
	v_pk_fma_f32 v[50:51], v[50:51], v[242:243], v[66:67] op_sel_hi:[1,0,1]
	v_pk_fma_f32 v[52:53], v[52:53], v[242:243], v[68:69] op_sel_hi:[1,0,1]
	v_pk_mul_f32 v[234:235], v[62:63], s[100:101] op_sel_hi:[1,0]
	v_pk_mul_f32 v[236:237], v[64:65], s[100:101] op_sel_hi:[1,0]
	v_exp_f32_e32 v234, v234
	v_exp_f32_e32 v235, v235
	v_exp_f32_e32 v236, v236
	v_exp_f32_e32 v237, v237
	v_pk_add_f32 v[234:235], v[234:235], 1.0 op_sel_hi:[1,0]
	v_pk_add_f32 v[236:237], v[236:237], 1.0 op_sel_hi:[1,0]
	v_rcp_f32_e32 v234, v234
	v_rcp_f32_e32 v235, v235
	v_rcp_f32_e32 v236, v236
	v_rcp_f32_e32 v237, v237
	v_pk_mul_f32 v[54:55], v[62:63], v[54:55]
	v_pk_mul_f32 v[56:57], v[64:65], v[56:57]
	v_pk_mul_f32 v[54:55], v[54:55], v[234:235]
	v_pk_mul_f32 v[56:57], v[56:57], v[236:237]
	v_cvt_pk_bf16_f32 v238, v54, v55
	v_cvt_pk_bf16_f32 v239, v56, v57
	v_pk_mul_f32 v[234:235], v[58:59], s[100:101] op_sel_hi:[1,0]
	v_pk_mul_f32 v[236:237], v[60:61], s[100:101] op_sel_hi:[1,0]
	v_exp_f32_e32 v234, v234
	v_exp_f32_e32 v235, v235
	v_exp_f32_e32 v236, v236
	v_exp_f32_e32 v237, v237
	v_pk_add_f32 v[234:235], v[234:235], 1.0 op_sel_hi:[1,0]
	v_pk_add_f32 v[236:237], v[236:237], 1.0 op_sel_hi:[1,0]
	v_rcp_f32_e32 v234, v234
	v_rcp_f32_e32 v235, v235
	v_rcp_f32_e32 v236, v236
	v_rcp_f32_e32 v237, v237
	v_pk_mul_f32 v[50:51], v[58:59], v[50:51]
	v_pk_mul_f32 v[52:53], v[60:61], v[52:53]
	v_pk_mul_f32 v[50:51], v[50:51], v[234:235]
	v_pk_mul_f32 v[52:53], v[52:53], v[236:237]
	v_cvt_pk_bf16_f32 v240, v50, v51
	v_cvt_pk_bf16_f32 v241, v52, v53
	global_store_dwordx4 v[86:87], v[238:241], off
	v_add_u32_e32 v51, 0x90, v181
	v_mad_i64_i32 v[52:53], s[2:3], v51, s49, v[162:163]
	v_lshl_add_u64 v[52:53], v[52:53], 0, v[164:165]
	v_pk_fma_f32 v[46:47], v[46:47], v[244:245], v[78:79] op_sel_hi:[1,0,1]
	v_pk_fma_f32 v[48:49], v[48:49], v[244:245], v[80:81] op_sel_hi:[1,0,1]
	v_pk_fma_f32 v[38:39], v[38:39], v[244:245], v[70:71] op_sel_hi:[1,0,1]
	v_pk_fma_f32 v[40:41], v[40:41], v[244:245], v[72:73] op_sel_hi:[1,0,1]
	v_pk_fma_f32 v[42:43], v[42:43], v[244:245], v[74:75] op_sel_hi:[1,0,1]
	v_pk_fma_f32 v[44:45], v[44:45], v[244:245], v[76:77] op_sel_hi:[1,0,1]
	v_pk_fma_f32 v[34:35], v[34:35], v[244:245], v[66:67] op_sel_hi:[1,0,1]
	v_pk_fma_f32 v[36:37], v[36:37], v[244:245], v[68:69] op_sel_hi:[1,0,1]
	v_pk_mul_f32 v[234:235], v[46:47], s[100:101] op_sel_hi:[1,0]
	v_pk_mul_f32 v[236:237], v[48:49], s[100:101] op_sel_hi:[1,0]
	v_exp_f32_e32 v234, v234
	v_exp_f32_e32 v235, v235
	v_exp_f32_e32 v236, v236
	v_exp_f32_e32 v237, v237
	v_pk_add_f32 v[234:235], v[234:235], 1.0 op_sel_hi:[1,0]
	v_pk_add_f32 v[236:237], v[236:237], 1.0 op_sel_hi:[1,0]
	v_rcp_f32_e32 v234, v234
	v_rcp_f32_e32 v235, v235
	v_rcp_f32_e32 v236, v236
	v_rcp_f32_e32 v237, v237
	v_pk_mul_f32 v[38:39], v[46:47], v[38:39]
	v_pk_mul_f32 v[40:41], v[48:49], v[40:41]
	v_pk_mul_f32 v[38:39], v[38:39], v[234:235]
	v_pk_mul_f32 v[40:41], v[40:41], v[236:237]
	v_cvt_pk_bf16_f32 v238, v38, v39
	v_cvt_pk_bf16_f32 v239, v40, v41
	v_pk_mul_f32 v[234:235], v[42:43], s[100:101] op_sel_hi:[1,0]
	v_pk_mul_f32 v[236:237], v[44:45], s[100:101] op_sel_hi:[1,0]
; __device__ __forceinline__ unsigned cvt_pk_bf16(float lo, float hi) { unsigned r; asm volatile("v_cvt_pk_bf16_f32 %0, %1, %2" : "=v"(r) : "v"(lo), "v"(hi)); return r; }
; __device__ __forceinline__ float silu_mul(float a, float b) { return a * b * __builtin_amdgcn_rcpf(1.0f + __builtin_amdgcn_exp2f(-a * LOG2E)); }
; #define PG8_BAR __builtin_amdgcn_s_barrier()
;     __device__ __forceinline__ void operator()(const f32x4 (&acc)[2][2][4][2], const Unit& u, int wr, int wc, int fr, int fq) const {
;     ...
;             for (int m = 0; m < 4; ++m) { const int row = row0 + ai * HALF + m * 16; const float rs = __shfl(ai ? rsl1 : rsl0, m * 16 + fr); bf16_t* rowp = O + (size_t)row * DFF + col0;
;                 const f32x4 a0 = acc[ai][0][m][0] * rs + ba0, a1 = acc[ai][0][m][1] * rs + ba1, b0 = acc[ai][1][m][0] * rs + bb0, b1 = acc[ai][1][m][1] * rs + bb1;
;                 u32x4 w; w.x = cvt_pk_bf16(silu_mul(a0[0], b0[0]), silu_mul(a0[1], b0[1])); w.y = cvt_pk_bf16(silu_mul(a0[2], b0[2]), silu_mul(a0[3], b0[3]));
;                 w.z = cvt_pk_bf16(silu_mul(a1[0], b1[0]), silu_mul(a1[1], b1[1])); w.w = cvt_pk_bf16(silu_mul(a1[2], b1[2]), silu_mul(a1[3], b1[3]));
;                 *(u32x4*)rowp = w; }
; template <class Epi, class Sched, bool ALIGN_EPI = false, bool SP2 = false>
; __device__ __forceinline__ void gemm_phase(LAS unsigned char* lds, const Gemm g, const Sched& S, const Epi& E) {
;     ...
;         if (!has_next) break;
; #pragma unroll
;         for (int a = 0; a < 2; ++a)
; #pragma unroll
;             for (int b = 0; b < 2; ++b)
; #pragma unroll
;                 for (int m = 0; m < 4; ++m)
; #pragma unroll
;                     for (int n = 0; n < 2; ++n) acc[a][b][m][n] = (f32x4){0.f, 0.f, 0.f, 0.f};
;         cur = nxt; cA = nA; cB = nB; ++ui;
;         if constexpr (ALIGN_EPI) { if (wr == 1) PG8_BAR; }
	v_exp_f32_e32 v234, v234
	v_exp_f32_e32 v235, v235
	v_exp_f32_e32 v236, v236
	v_exp_f32_e32 v237, v237
	v_pk_add_f32 v[234:235], v[234:235], 1.0 op_sel_hi:[1,0]
	v_pk_add_f32 v[236:237], v[236:237], 1.0 op_sel_hi:[1,0]
	v_rcp_f32_e32 v234, v234
	v_rcp_f32_e32 v235, v235
	v_rcp_f32_e32 v236, v236
	v_rcp_f32_e32 v237, v237
	v_pk_mul_f32 v[34:35], v[42:43], v[34:35]
	v_pk_mul_f32 v[36:37], v[44:45], v[36:37]
	v_pk_mul_f32 v[34:35], v[34:35], v[234:235]
	v_pk_mul_f32 v[36:37], v[36:37], v[236:237]
	v_cvt_pk_bf16_f32 v240, v34, v35
	v_cvt_pk_bf16_f32 v241, v36, v37
	global_store_dwordx4 v[52:53], v[238:241], off
	v_add_u32_e32 v35, 0xa0, v181
	v_mad_i64_i32 v[36:37], s[2:3], v35, s49, v[162:163]
	v_lshl_add_u64 v[36:37], v[36:37], 0, v[164:165]
	v_pk_fma_f32 v[30:31], v[30:31], v[246:247], v[78:79] op_sel_hi:[1,0,1]
	v_pk_fma_f32 v[32:33], v[32:33], v[246:247], v[80:81] op_sel_hi:[1,0,1]
	v_pk_fma_f32 v[22:23], v[22:23], v[246:247], v[70:71] op_sel_hi:[1,0,1]
	v_pk_fma_f32 v[24:25], v[24:25], v[246:247], v[72:73] op_sel_hi:[1,0,1]
	v_pk_fma_f32 v[26:27], v[26:27], v[246:247], v[74:75] op_sel_hi:[1,0,1]
	v_pk_fma_f32 v[28:29], v[28:29], v[246:247], v[76:77] op_sel_hi:[1,0,1]
	v_pk_fma_f32 v[18:19], v[18:19], v[246:247], v[66:67] op_sel_hi:[1,0,1]
	v_pk_fma_f32 v[20:21], v[20:21], v[246:247], v[68:69] op_sel_hi:[1,0,1]
	v_pk_mul_f32 v[234:235], v[30:31], s[100:101] op_sel_hi:[1,0]
	v_pk_mul_f32 v[236:237], v[32:33], s[100:101] op_sel_hi:[1,0]
	v_exp_f32_e32 v234, v234
	v_exp_f32_e32 v235, v235
	v_exp_f32_e32 v236, v236
	v_exp_f32_e32 v237, v237
	v_pk_add_f32 v[234:235], v[234:235], 1.0 op_sel_hi:[1,0]
	v_pk_add_f32 v[236:237], v[236:237], 1.0 op_sel_hi:[1,0]
	v_rcp_f32_e32 v234, v234
	v_rcp_f32_e32 v235, v235
	v_rcp_f32_e32 v236, v236
	v_rcp_f32_e32 v237, v237
	v_pk_mul_f32 v[22:23], v[30:31], v[22:23]
	v_pk_mul_f32 v[24:25], v[32:33], v[24:25]
	v_pk_mul_f32 v[22:23], v[22:23], v[234:235]
	v_pk_mul_f32 v[24:25], v[24:25], v[236:237]
	v_cvt_pk_bf16_f32 v238, v22, v23
	v_cvt_pk_bf16_f32 v239, v24, v25
	v_pk_mul_f32 v[234:235], v[26:27], s[100:101] op_sel_hi:[1,0]
	v_pk_mul_f32 v[236:237], v[28:29], s[100:101] op_sel_hi:[1,0]
	v_exp_f32_e32 v234, v234
	v_exp_f32_e32 v235, v235
	v_exp_f32_e32 v236, v236
	v_exp_f32_e32 v237, v237
	v_pk_add_f32 v[234:235], v[234:235], 1.0 op_sel_hi:[1,0]
	v_pk_add_f32 v[236:237], v[236:237], 1.0 op_sel_hi:[1,0]
	v_rcp_f32_e32 v234, v234
	v_rcp_f32_e32 v235, v235
	v_rcp_f32_e32 v236, v236
	v_rcp_f32_e32 v237, v237
	v_pk_mul_f32 v[18:19], v[26:27], v[18:19]
	v_pk_mul_f32 v[20:21], v[28:29], v[20:21]
	v_pk_mul_f32 v[18:19], v[18:19], v[234:235]
	v_pk_mul_f32 v[20:21], v[20:21], v[236:237]
	v_cvt_pk_bf16_f32 v240, v18, v19
	v_cvt_pk_bf16_f32 v241, v20, v21
	global_store_dwordx4 v[36:37], v[238:241], off
	v_add_u32_e32 v19, 0xb0, v181
	v_mad_i64_i32 v[20:21], s[2:3], v19, s49, v[162:163]
	v_lshl_add_u64 v[20:21], v[20:21], 0, v[164:165]
	s_mov_b64 s[2:3], -1
	v_pk_fma_f32 v[14:15], v[14:15], v[248:249], v[78:79] op_sel_hi:[1,0,1]
	v_pk_fma_f32 v[16:17], v[16:17], v[248:249], v[80:81] op_sel_hi:[1,0,1]
	v_pk_fma_f32 v[6:7], v[6:7], v[248:249], v[70:71] op_sel_hi:[1,0,1]
	v_pk_fma_f32 v[8:9], v[8:9], v[248:249], v[72:73] op_sel_hi:[1,0,1]
	v_pk_fma_f32 v[10:11], v[10:11], v[248:249], v[74:75] op_sel_hi:[1,0,1]
	v_pk_fma_f32 v[12:13], v[12:13], v[248:249], v[76:77] op_sel_hi:[1,0,1]
	v_pk_fma_f32 v[2:3], v[2:3], v[248:249], v[66:67] op_sel_hi:[1,0,1]
	v_pk_fma_f32 v[4:5], v[4:5], v[248:249], v[68:69] op_sel_hi:[1,0,1]
	v_pk_mul_f32 v[234:235], v[14:15], s[100:101] op_sel_hi:[1,0]
	v_pk_mul_f32 v[236:237], v[16:17], s[100:101] op_sel_hi:[1,0]
	v_exp_f32_e32 v234, v234
	v_exp_f32_e32 v235, v235
	v_exp_f32_e32 v236, v236
	v_exp_f32_e32 v237, v237
	v_pk_add_f32 v[234:235], v[234:235], 1.0 op_sel_hi:[1,0]
	v_pk_add_f32 v[236:237], v[236:237], 1.0 op_sel_hi:[1,0]
	v_rcp_f32_e32 v234, v234
	v_rcp_f32_e32 v235, v235
	v_rcp_f32_e32 v236, v236
	v_rcp_f32_e32 v237, v237
	v_pk_mul_f32 v[6:7], v[14:15], v[6:7]
	v_pk_mul_f32 v[8:9], v[16:17], v[8:9]
	v_pk_mul_f32 v[6:7], v[6:7], v[234:235]
	v_pk_mul_f32 v[8:9], v[8:9], v[236:237]
	v_cvt_pk_bf16_f32 v238, v6, v7
	v_cvt_pk_bf16_f32 v239, v8, v9
	v_pk_mul_f32 v[234:235], v[10:11], s[100:101] op_sel_hi:[1,0]
	v_pk_mul_f32 v[236:237], v[12:13], s[100:101] op_sel_hi:[1,0]
	v_exp_f32_e32 v234, v234
	v_exp_f32_e32 v235, v235
	v_exp_f32_e32 v236, v236
	v_exp_f32_e32 v237, v237
	v_pk_add_f32 v[234:235], v[234:235], 1.0 op_sel_hi:[1,0]
	v_pk_add_f32 v[236:237], v[236:237], 1.0 op_sel_hi:[1,0]
	v_rcp_f32_e32 v234, v234
	v_rcp_f32_e32 v235, v235
	v_rcp_f32_e32 v236, v236
	v_rcp_f32_e32 v237, v237
	v_pk_mul_f32 v[2:3], v[10:11], v[2:3]
	v_pk_mul_f32 v[4:5], v[12:13], v[4:5]
	v_pk_mul_f32 v[2:3], v[2:3], v[234:235]
	v_pk_mul_f32 v[4:5], v[4:5], v[236:237]
	v_cvt_pk_bf16_f32 v240, v2, v3
	v_cvt_pk_bf16_f32 v241, v4, v5
	global_store_dwordx4 v[20:21], v[238:241], off
	s_waitcnt vmcnt(8)
	s_setprio 0
	s_cbranch_vccnz .LBB0_1461
	s_andn2_b64 vcc, exec, s[4:5]
	s_cbranch_vccnz .LBB0_1460
	s_barrier
	s_branch .LBB0_1460

; __device__ __forceinline__ unsigned cvt_pk_bf16(float lo, float hi) { unsigned r; asm volatile("v_cvt_pk_bf16_f32 %0, %1, %2" : "=v"(r) : "v"(lo), "v"(hi)); return r; }
; __device__ __forceinline__ float row_rstd(const float* ss, int row) { return 1.0f / sqrtf(ss[row] * (1.0f / DM) + 1e-6f); }
; __device__ __forceinline__ float silu_mul(float a, float b) { return a * b * __builtin_amdgcn_rcpf(1.0f + __builtin_amdgcn_exp2f(-a * LOG2E)); }
; #define PG8_BAR __builtin_amdgcn_s_barrier()
;     __device__ __forceinline__ void operator()(const f32x4 (&acc)[2][2][4][2], const Unit& u, int wr, int wc, int fr, int fq) const {
;         const int row0 = u.pm * BM + wr * 64 + fr, col0 = u.pn * HALF + wc * 32 + 8 * fq;
;         const int s = (u.pm < ML / BM) ? (u.pm >> 5) : 4;
;         const float* bp = bias + (size_t)s * BIAS_N + u.pn * BM + wc * 32 + 8 * fq;
;         const f32x4 ba0 = *(const f32x4*)bp, ba1 = *(const f32x4*)(bp + 4), bb0 = *(const f32x4*)(bp + HALF), bb1 = *(const f32x4*)(bp + HALF + 4);
;         const int lane = fq * 16 + fr;
;         const float rsl0 = row_rstd(ss, u.pm * BM + wr * 64 + lane), rsl1 = row_rstd(ss, u.pm * BM + HALF + wr * 64 + lane);
; #pragma unroll
;         for (int ai = 0; ai < 2; ++ai)
; #pragma unroll
;             for (int m = 0; m < 4; ++m) { const int row = row0 + ai * HALF + m * 16; const float rs = __shfl(ai ? rsl1 : rsl0, m * 16 + fr); bf16_t* rowp = O + (size_t)row * DFF + col0;
;                 const f32x4 a0 = acc[ai][0][m][0] * rs + ba0, a1 = acc[ai][0][m][1] * rs + ba1, b0 = acc[ai][1][m][0] * rs + bb0, b1 = acc[ai][1][m][1] * rs + bb1;
;                 u32x4 w; w.x = cvt_pk_bf16(silu_mul(a0[0], b0[0]), silu_mul(a0[1], b0[1])); w.y = cvt_pk_bf16(silu_mul(a0[2], b0[2]), silu_mul(a0[3], b0[3]));
;                 w.z = cvt_pk_bf16(silu_mul(a1[0], b1[0]), silu_mul(a1[1], b1[1])); w.w = cvt_pk_bf16(silu_mul(a1[2], b1[2]), silu_mul(a1[3], b1[3]));
;                 *(u32x4*)rowp = w; }
; template <class Epi, class Sched, bool ALIGN_EPI = false, bool SP2 = false>
; __device__ __forceinline__ void gemm_phase(LAS unsigned char* lds, const Gemm g, const Sched& S, const Epi& E) {
;     ...
;         if constexpr (ALIGN_EPI) { if (wr == 0) PG8_BAR; }
.LBB0_1827:
	s_lshl_b32 s2, s2, 8
	s_add_i32 s13, s2, s35
	s_lshl_b64 s[2:3], s[16:17], 2
	s_add_u32 s15, s36, s2
	s_addc_u32 s16, s37, s3
	s_lshl_b32 s2, s0, 8
	s_ashr_i32 s3, s2, 31
	s_lshl_b64 s[2:3], s[2:3], 2
	v_lshl_or_b32 v164, s0, 7, v172
	s_add_u32 s0, s15, s2
	s_addc_u32 s3, s16, s3
	v_or_b32_e32 v162, s13, v170
	s_add_u32 s2, s0, s47
	v_ashrrev_i32_e32 v163, 31, v162
	s_addc_u32 s3, s3, 0
	v_lshl_add_u64 v[162:163], v[162:163], 2, s[6:7]
	v_mov_b32_e32 v74, v234
	v_mov_b32_e32 v75, v235
	v_mov_b32_e32 v76, v236
	v_mov_b32_e32 v77, v237
	v_mov_b32_e32 v78, v238
	v_mov_b32_e32 v79, v239
	v_mov_b32_e32 v80, v240
	v_mov_b32_e32 v81, v241
	v_mov_b32_e32 v66, v242
	v_mov_b32_e32 v67, v243
	v_mov_b32_e32 v68, v244
	v_mov_b32_e32 v69, v245
	v_mov_b32_e32 v70, v246
	v_mov_b32_e32 v71, v247
	v_mov_b32_e32 v72, v248
	v_mov_b32_e32 v73, v249
	v_or_b32_e32 v180, s13, v1
	v_mov_b32_e32 v162, v250
	v_fmamk_f32 v162, v162, 0x3a000000, v177
	v_cmp_gt_f32_e32 vcc, s48, v162
	v_mul_f32_e32 v163, 0x4f800000, v162
	s_nop 0
	v_cndmask_b32_e32 v162, v162, v163, vcc
	v_sqrt_f32_e32 v163, v162
	s_nop 0
	v_add_u32_e32 v165, -1, v163
	v_fma_f32 v166, -v165, v163, v162
	v_cmp_ge_f32_e64 s[2:3], 0, v166
	v_add_u32_e32 v166, 1, v163
	s_nop 0
	v_cndmask_b32_e64 v165, v163, v165, s[2:3]
	v_fma_f32 v163, -v166, v163, v162
	v_cmp_lt_f32_e64 s[2:3], 0, v163
	s_nop 1
	v_cndmask_b32_e64 v163, v165, v166, s[2:3]
	v_mul_f32_e32 v165, 0x37800000, v163
	v_cndmask_b32_e32 v163, v163, v165, vcc
	v_cmp_class_f32_e32 vcc, v162, v178
	s_nop 1
	v_cndmask_b32_e32 v166, v163, v162, vcc
	v_add_u32_e32 v162, s13, v171
	v_ashrrev_i32_e32 v163, 31, v162
	v_lshl_add_u64 v[162:163], v[162:163], 2, s[6:7]
	v_mov_b32_e32 v162, v251
	v_fmamk_f32 v162, v162, 0x3a000000, v177
	v_cmp_gt_f32_e32 vcc, s48, v162
	v_mul_f32_e32 v163, 0x4f800000, v162
	s_nop 0
	v_cndmask_b32_e32 v162, v162, v163, vcc
	v_sqrt_f32_e32 v163, v162
	s_nop 0
	v_add_u32_e32 v165, -1, v163
	v_fma_f32 v167, -v165, v163, v162
	v_cmp_ge_f32_e64 s[2:3], 0, v167
	v_add_u32_e32 v167, 1, v163
	s_nop 0
	v_cndmask_b32_e64 v165, v163, v165, s[2:3]
	v_fma_f32 v163, -v167, v163, v162
	v_cmp_lt_f32_e64 s[2:3], 0, v163
	s_nop 1
	v_cndmask_b32_e64 v163, v165, v167, s[2:3]
	v_mul_f32_e32 v165, 0x37800000, v163
	v_cndmask_b32_e32 v163, v163, v165, vcc
	v_cmp_class_f32_e32 vcc, v162, v178
	v_ashrrev_i32_e32 v165, 31, v164
	v_lshlrev_b64 v[164:165], 1, v[164:165]
	v_cndmask_b32_e32 v181, v163, v162, vcc
	v_div_scale_f32 v162, s[2:3], v166, v166, 1.0
	v_rcp_f32_e32 v163, v162
	s_nop 0
	v_fma_f32 v167, -v162, v163, 1.0
	v_fmac_f32_e32 v163, v167, v163
	v_div_scale_f32 v167, vcc, 1.0, v166, 1.0
	v_mul_f32_e32 v168, v167, v163
	v_fma_f32 v182, -v162, v168, v167
	v_fmac_f32_e32 v168, v182, v163
	v_fma_f32 v162, -v162, v168, v167
	v_div_fmas_f32 v162, v162, v163, v168
	v_div_fixup_f32 v182, v162, v166, 1.0
	s_andn2_b64 vcc, exec, s[10:11]
	s_cbranch_vccnz .Lalign_1825
	s_barrier
	s_setprio 1
.Lalign_1825:
	s_mov_b32 s100, 0xbfb8aa3b
	ds_bpermute_b32 v242, v179, v182
	ds_bpermute_b32 v244, v179, v182 offset:64
	ds_bpermute_b32 v246, v179, v182 offset:128
	ds_bpermute_b32 v248, v179, v182 offset:192
	v_mov_b64_e32 v[162:163], s[96:97]
	v_mad_i64_i32 v[166:167], s[2:3], v180, s46, v[162:163]
	v_lshl_add_u64 v[166:167], v[166:167], 0, v[164:165]
	s_waitcnt lgkmcnt(0)
	v_pk_fma_f32 v[142:143], v[142:143], v[242:243], v[78:79] op_sel_hi:[1,0,1]
	v_pk_fma_f32 v[144:145], v[144:145], v[242:243], v[80:81] op_sel_hi:[1,0,1]
	v_pk_fma_f32 v[134:135], v[134:135], v[242:243], v[70:71] op_sel_hi:[1,0,1]
	v_pk_fma_f32 v[136:137], v[136:137], v[242:243], v[72:73] op_sel_hi:[1,0,1]
	v_pk_fma_f32 v[138:139], v[138:139], v[242:243], v[74:75] op_sel_hi:[1,0,1]
	v_pk_fma_f32 v[140:141], v[140:141], v[242:243], v[76:77] op_sel_hi:[1,0,1]
	v_pk_fma_f32 v[130:131], v[130:131], v[242:243], v[66:67] op_sel_hi:[1,0,1]
	v_pk_fma_f32 v[132:133], v[132:133], v[242:243], v[68:69] op_sel_hi:[1,0,1]
	v_pk_mul_f32 v[234:235], v[142:143], s[100:101] op_sel_hi:[1,0]
	v_pk_mul_f32 v[236:237], v[144:145], s[100:101] op_sel_hi:[1,0]
	v_exp_f32_e32 v234, v234
	v_exp_f32_e32 v235, v235
	v_exp_f32_e32 v236, v236
	v_exp_f32_e32 v237, v237
	v_pk_add_f32 v[234:235], v[234:235], 1.0 op_sel_hi:[1,0]
	v_pk_add_f32 v[236:237], v[236:237], 1.0 op_sel_hi:[1,0]
	v_rcp_f32_e32 v234, v234
	v_rcp_f32_e32 v235, v235
	v_rcp_f32_e32 v236, v236
	v_rcp_f32_e32 v237, v237
	v_pk_mul_f32 v[134:135], v[142:143], v[134:135]
	v_pk_mul_f32 v[136:137], v[144:145], v[136:137]
	v_pk_mul_f32 v[134:135], v[134:135], v[234:235]
	v_pk_mul_f32 v[136:137], v[136:137], v[236:237]
	v_cvt_pk_bf16_f32 v238, v134, v135
	v_cvt_pk_bf16_f32 v239, v136, v137
	v_pk_mul_f32 v[234:235], v[138:139], s[100:101] op_sel_hi:[1,0]
	v_pk_mul_f32 v[236:237], v[140:141], s[100:101] op_sel_hi:[1,0]
	v_exp_f32_e32 v234, v234
	v_exp_f32_e32 v235, v235
	v_exp_f32_e32 v236, v236
	v_exp_f32_e32 v237, v237
	v_pk_add_f32 v[234:235], v[234:235], 1.0 op_sel_hi:[1,0]
	v_pk_add_f32 v[236:237], v[236:237], 1.0 op_sel_hi:[1,0]
	v_rcp_f32_e32 v234, v234
	v_rcp_f32_e32 v235, v235
	v_rcp_f32_e32 v236, v236
	v_rcp_f32_e32 v237, v237
	v_pk_mul_f32 v[130:131], v[138:139], v[130:131]
	v_pk_mul_f32 v[132:133], v[140:141], v[132:133]
	v_pk_mul_f32 v[130:131], v[130:131], v[234:235]
	v_pk_mul_f32 v[132:133], v[132:133], v[236:237]
	v_cvt_pk_bf16_f32 v240, v130, v131
	v_cvt_pk_bf16_f32 v241, v132, v133
	global_store_dwordx4 v[166:167], v[238:241], off
	v_or_b32_e32 v131, 16, v180
	v_mad_i64_i32 v[132:133], s[2:3], v131, s46, v[162:163]
	v_lshl_add_u64 v[132:133], v[132:133], 0, v[164:165]
	v_pk_fma_f32 v[126:127], v[126:127], v[244:245], v[78:79] op_sel_hi:[1,0,1]
; __device__ __forceinline__ unsigned cvt_pk_bf16(float lo, float hi) { unsigned r; asm volatile("v_cvt_pk_bf16_f32 %0, %1, %2" : "=v"(r) : "v"(lo), "v"(hi)); return r; }
; __device__ __forceinline__ float silu_mul(float a, float b) { return a * b * __builtin_amdgcn_rcpf(1.0f + __builtin_amdgcn_exp2f(-a * LOG2E)); }
;     __device__ __forceinline__ void operator()(const f32x4 (&acc)[2][2][4][2], const Unit& u, int wr, int wc, int fr, int fq) const {
;     ...
;             for (int m = 0; m < 4; ++m) { const int row = row0 + ai * HALF + m * 16; const float rs = __shfl(ai ? rsl1 : rsl0, m * 16 + fr); bf16_t* rowp = O + (size_t)row * DFF + col0;
;                 const f32x4 a0 = acc[ai][0][m][0] * rs + ba0, a1 = acc[ai][0][m][1] * rs + ba1, b0 = acc[ai][1][m][0] * rs + bb0, b1 = acc[ai][1][m][1] * rs + bb1;
;                 u32x4 w; w.x = cvt_pk_bf16(silu_mul(a0[0], b0[0]), silu_mul(a0[1], b0[1])); w.y = cvt_pk_bf16(silu_mul(a0[2], b0[2]), silu_mul(a0[3], b0[3]));
;                 w.z = cvt_pk_bf16(silu_mul(a1[0], b1[0]), silu_mul(a1[1], b1[1])); w.w = cvt_pk_bf16(silu_mul(a1[2], b1[2]), silu_mul(a1[3], b1[3]));
;                 *(u32x4*)rowp = w; }
	v_pk_fma_f32 v[128:129], v[128:129], v[244:245], v[80:81] op_sel_hi:[1,0,1]
	v_pk_fma_f32 v[118:119], v[118:119], v[244:245], v[70:71] op_sel_hi:[1,0,1]
	v_pk_fma_f32 v[120:121], v[120:121], v[244:245], v[72:73] op_sel_hi:[1,0,1]
	v_pk_fma_f32 v[122:123], v[122:123], v[244:245], v[74:75] op_sel_hi:[1,0,1]
	v_pk_fma_f32 v[124:125], v[124:125], v[244:245], v[76:77] op_sel_hi:[1,0,1]
	v_pk_fma_f32 v[114:115], v[114:115], v[244:245], v[66:67] op_sel_hi:[1,0,1]
	v_pk_fma_f32 v[116:117], v[116:117], v[244:245], v[68:69] op_sel_hi:[1,0,1]
	v_pk_mul_f32 v[234:235], v[126:127], s[100:101] op_sel_hi:[1,0]
	v_pk_mul_f32 v[236:237], v[128:129], s[100:101] op_sel_hi:[1,0]
	v_exp_f32_e32 v234, v234
	v_exp_f32_e32 v235, v235
	v_exp_f32_e32 v236, v236
	v_exp_f32_e32 v237, v237
	v_pk_add_f32 v[234:235], v[234:235], 1.0 op_sel_hi:[1,0]
	v_pk_add_f32 v[236:237], v[236:237], 1.0 op_sel_hi:[1,0]
	v_rcp_f32_e32 v234, v234
	v_rcp_f32_e32 v235, v235
	v_rcp_f32_e32 v236, v236
	v_rcp_f32_e32 v237, v237
	v_pk_mul_f32 v[118:119], v[126:127], v[118:119]
	v_pk_mul_f32 v[120:121], v[128:129], v[120:121]
	v_pk_mul_f32 v[118:119], v[118:119], v[234:235]
	v_pk_mul_f32 v[120:121], v[120:121], v[236:237]
	v_cvt_pk_bf16_f32 v238, v118, v119
	v_cvt_pk_bf16_f32 v239, v120, v121
	v_pk_mul_f32 v[234:235], v[122:123], s[100:101] op_sel_hi:[1,0]
	v_pk_mul_f32 v[236:237], v[124:125], s[100:101] op_sel_hi:[1,0]
	v_exp_f32_e32 v234, v234
	v_exp_f32_e32 v235, v235
	v_exp_f32_e32 v236, v236
	v_exp_f32_e32 v237, v237
	v_pk_add_f32 v[234:235], v[234:235], 1.0 op_sel_hi:[1,0]
	v_pk_add_f32 v[236:237], v[236:237], 1.0 op_sel_hi:[1,0]
	v_rcp_f32_e32 v234, v234
	v_rcp_f32_e32 v235, v235
	v_rcp_f32_e32 v236, v236
	v_rcp_f32_e32 v237, v237
	v_pk_mul_f32 v[114:115], v[122:123], v[114:115]
	v_pk_mul_f32 v[116:117], v[124:125], v[116:117]
	v_pk_mul_f32 v[114:115], v[114:115], v[234:235]
	v_pk_mul_f32 v[116:117], v[116:117], v[236:237]
	v_cvt_pk_bf16_f32 v240, v114, v115
	v_cvt_pk_bf16_f32 v241, v116, v117
	global_store_dwordx4 v[132:133], v[238:241], off
	v_or_b32_e32 v115, 32, v180
	v_mad_i64_i32 v[116:117], s[2:3], v115, s46, v[162:163]
	v_lshl_add_u64 v[116:117], v[116:117], 0, v[164:165]
	v_pk_fma_f32 v[110:111], v[110:111], v[246:247], v[78:79] op_sel_hi:[1,0,1]
	v_pk_fma_f32 v[112:113], v[112:113], v[246:247], v[80:81] op_sel_hi:[1,0,1]
	v_pk_fma_f32 v[102:103], v[102:103], v[246:247], v[70:71] op_sel_hi:[1,0,1]
	v_pk_fma_f32 v[104:105], v[104:105], v[246:247], v[72:73] op_sel_hi:[1,0,1]
	v_pk_fma_f32 v[106:107], v[106:107], v[246:247], v[74:75] op_sel_hi:[1,0,1]
	v_pk_fma_f32 v[108:109], v[108:109], v[246:247], v[76:77] op_sel_hi:[1,0,1]
	v_pk_fma_f32 v[98:99], v[98:99], v[246:247], v[66:67] op_sel_hi:[1,0,1]
	v_pk_fma_f32 v[100:101], v[100:101], v[246:247], v[68:69] op_sel_hi:[1,0,1]
	v_pk_mul_f32 v[234:235], v[110:111], s[100:101] op_sel_hi:[1,0]
	v_pk_mul_f32 v[236:237], v[112:113], s[100:101] op_sel_hi:[1,0]
	v_exp_f32_e32 v234, v234
	v_exp_f32_e32 v235, v235
	v_exp_f32_e32 v236, v236
	v_exp_f32_e32 v237, v237
	v_pk_add_f32 v[234:235], v[234:235], 1.0 op_sel_hi:[1,0]
	v_pk_add_f32 v[236:237], v[236:237], 1.0 op_sel_hi:[1,0]
	v_rcp_f32_e32 v234, v234
	v_rcp_f32_e32 v235, v235
	v_rcp_f32_e32 v236, v236
	v_rcp_f32_e32 v237, v237
	v_pk_mul_f32 v[102:103], v[110:111], v[102:103]
	v_pk_mul_f32 v[104:105], v[112:113], v[104:105]
	v_pk_mul_f32 v[102:103], v[102:103], v[234:235]
	v_pk_mul_f32 v[104:105], v[104:105], v[236:237]
	v_cvt_pk_bf16_f32 v238, v102, v103
	v_cvt_pk_bf16_f32 v239, v104, v105
	v_pk_mul_f32 v[234:235], v[106:107], s[100:101] op_sel_hi:[1,0]
	v_pk_mul_f32 v[236:237], v[108:109], s[100:101] op_sel_hi:[1,0]
	v_exp_f32_e32 v234, v234
	v_exp_f32_e32 v235, v235
	v_exp_f32_e32 v236, v236
	v_exp_f32_e32 v237, v237
	v_pk_add_f32 v[234:235], v[234:235], 1.0 op_sel_hi:[1,0]
	v_pk_add_f32 v[236:237], v[236:237], 1.0 op_sel_hi:[1,0]
	v_rcp_f32_e32 v234, v234
	v_rcp_f32_e32 v235, v235
	v_rcp_f32_e32 v236, v236
	v_rcp_f32_e32 v237, v237
	v_pk_mul_f32 v[98:99], v[106:107], v[98:99]
	v_pk_mul_f32 v[100:101], v[108:109], v[100:101]
	v_pk_mul_f32 v[98:99], v[98:99], v[234:235]
	v_pk_mul_f32 v[100:101], v[100:101], v[236:237]
	v_cvt_pk_bf16_f32 v240, v98, v99
	v_cvt_pk_bf16_f32 v241, v100, v101
	global_store_dwordx4 v[116:117], v[238:241], off
	v_or_b32_e32 v99, 48, v180
	v_mad_i64_i32 v[100:101], s[2:3], v99, s46, v[162:163]
	v_lshl_add_u64 v[100:101], v[100:101], 0, v[164:165]
	v_pk_fma_f32 v[94:95], v[94:95], v[248:249], v[78:79] op_sel_hi:[1,0,1]
	v_pk_fma_f32 v[96:97], v[96:97], v[248:249], v[80:81] op_sel_hi:[1,0,1]
	v_pk_fma_f32 v[86:87], v[86:87], v[248:249], v[70:71] op_sel_hi:[1,0,1]
	v_pk_fma_f32 v[88:89], v[88:89], v[248:249], v[72:73] op_sel_hi:[1,0,1]
	v_pk_fma_f32 v[90:91], v[90:91], v[248:249], v[74:75] op_sel_hi:[1,0,1]
	v_pk_fma_f32 v[92:93], v[92:93], v[248:249], v[76:77] op_sel_hi:[1,0,1]
	v_pk_fma_f32 v[82:83], v[82:83], v[248:249], v[66:67] op_sel_hi:[1,0,1]
	v_pk_fma_f32 v[84:85], v[84:85], v[248:249], v[68:69] op_sel_hi:[1,0,1]
	v_pk_mul_f32 v[234:235], v[94:95], s[100:101] op_sel_hi:[1,0]
	v_pk_mul_f32 v[236:237], v[96:97], s[100:101] op_sel_hi:[1,0]
	v_exp_f32_e32 v234, v234
	v_exp_f32_e32 v235, v235
	v_exp_f32_e32 v236, v236
	v_exp_f32_e32 v237, v237
	v_pk_add_f32 v[234:235], v[234:235], 1.0 op_sel_hi:[1,0]
	v_pk_add_f32 v[236:237], v[236:237], 1.0 op_sel_hi:[1,0]
	v_rcp_f32_e32 v234, v234
	v_rcp_f32_e32 v235, v235
	v_rcp_f32_e32 v236, v236
	v_rcp_f32_e32 v237, v237
	v_pk_mul_f32 v[86:87], v[94:95], v[86:87]
	v_pk_mul_f32 v[88:89], v[96:97], v[88:89]
	v_pk_mul_f32 v[86:87], v[86:87], v[234:235]
	v_pk_mul_f32 v[88:89], v[88:89], v[236:237]
	v_cvt_pk_bf16_f32 v238, v86, v87
; __device__ __forceinline__ unsigned cvt_pk_bf16(float lo, float hi) { unsigned r; asm volatile("v_cvt_pk_bf16_f32 %0, %1, %2" : "=v"(r) : "v"(lo), "v"(hi)); return r; }
; __device__ __forceinline__ float row_rstd(const float* ss, int row) { return 1.0f / sqrtf(ss[row] * (1.0f / DM) + 1e-6f); }
; __device__ __forceinline__ float silu_mul(float a, float b) { return a * b * __builtin_amdgcn_rcpf(1.0f + __builtin_amdgcn_exp2f(-a * LOG2E)); }
;     __device__ __forceinline__ void operator()(const f32x4 (&acc)[2][2][4][2], const Unit& u, int wr, int wc, int fr, int fq) const {
;     ...
;         const float rsl0 = row_rstd(ss, u.pm * BM + wr * 64 + lane), rsl1 = row_rstd(ss, u.pm * BM + HALF + wr * 64 + lane);
; #pragma unroll
;         for (int ai = 0; ai < 2; ++ai)
; #pragma unroll
;             for (int m = 0; m < 4; ++m) { const int row = row0 + ai * HALF + m * 16; const float rs = __shfl(ai ? rsl1 : rsl0, m * 16 + fr); bf16_t* rowp = O + (size_t)row * DFF + col0;
;                 const f32x4 a0 = acc[ai][0][m][0] * rs + ba0, a1 = acc[ai][0][m][1] * rs + ba1, b0 = acc[ai][1][m][0] * rs + bb0, b1 = acc[ai][1][m][1] * rs + bb1;
;                 u32x4 w; w.x = cvt_pk_bf16(silu_mul(a0[0], b0[0]), silu_mul(a0[1], b0[1])); w.y = cvt_pk_bf16(silu_mul(a0[2], b0[2]), silu_mul(a0[3], b0[3]));
;                 w.z = cvt_pk_bf16(silu_mul(a1[0], b1[0]), silu_mul(a1[1], b1[1])); w.w = cvt_pk_bf16(silu_mul(a1[2], b1[2]), silu_mul(a1[3], b1[3]));
;                 *(u32x4*)rowp = w; }
	v_cvt_pk_bf16_f32 v239, v88, v89
	v_pk_mul_f32 v[234:235], v[90:91], s[100:101] op_sel_hi:[1,0]
	v_pk_mul_f32 v[236:237], v[92:93], s[100:101] op_sel_hi:[1,0]
	v_exp_f32_e32 v234, v234
	v_exp_f32_e32 v235, v235
	v_exp_f32_e32 v236, v236
	v_exp_f32_e32 v237, v237
	v_pk_add_f32 v[234:235], v[234:235], 1.0 op_sel_hi:[1,0]
	v_pk_add_f32 v[236:237], v[236:237], 1.0 op_sel_hi:[1,0]
	v_rcp_f32_e32 v234, v234
	v_rcp_f32_e32 v235, v235
	v_rcp_f32_e32 v236, v236
	v_rcp_f32_e32 v237, v237
	v_pk_mul_f32 v[82:83], v[90:91], v[82:83]
	v_pk_mul_f32 v[84:85], v[92:93], v[84:85]
	v_pk_mul_f32 v[82:83], v[82:83], v[234:235]
	v_pk_mul_f32 v[84:85], v[84:85], v[236:237]
	v_cvt_pk_bf16_f32 v240, v82, v83
	v_cvt_pk_bf16_f32 v241, v84, v85
	global_store_dwordx4 v[100:101], v[238:241], off
	s_nop 1
	v_div_scale_f32 v82, s[2:3], v181, v181, 1.0
	v_rcp_f32_e32 v84, v82
	v_add_u32_e32 v83, 0x80, v180
	v_fma_f32 v85, -v82, v84, 1.0
	v_fmac_f32_e32 v84, v85, v84
	v_div_scale_f32 v85, vcc, 1.0, v181, 1.0
	v_mul_f32_e32 v86, v85, v84
	v_fma_f32 v87, -v82, v86, v85
	v_fmac_f32_e32 v86, v87, v84
	v_fma_f32 v82, -v82, v86, v85
	v_div_fmas_f32 v82, v82, v84, v86
	v_div_fixup_f32 v82, v82, v181, 1.0
	ds_bpermute_b32 v242, v179, v82
	ds_bpermute_b32 v244, v179, v82 offset:64
	ds_bpermute_b32 v246, v179, v82 offset:128
	ds_bpermute_b32 v248, v179, v82 offset:192
	v_mad_i64_i32 v[86:87], s[2:3], v83, s46, v[162:163]
	v_lshl_add_u64 v[86:87], v[86:87], 0, v[164:165]
	s_and_b64 vcc, s[38:39], exec
	s_waitcnt lgkmcnt(0)
	v_pk_fma_f32 v[62:63], v[62:63], v[242:243], v[78:79] op_sel_hi:[1,0,1]
	v_pk_fma_f32 v[64:65], v[64:65], v[242:243], v[80:81] op_sel_hi:[1,0,1]
	v_pk_fma_f32 v[54:55], v[54:55], v[242:243], v[70:71] op_sel_hi:[1,0,1]
	v_pk_fma_f32 v[56:57], v[56:57], v[242:243], v[72:73] op_sel_hi:[1,0,1]
	v_pk_fma_f32 v[58:59], v[58:59], v[242:243], v[74:75] op_sel_hi:[1,0,1]
	v_pk_fma_f32 v[60:61], v[60:61], v[242:243], v[76:77] op_sel_hi:[1,0,1]
	v_pk_fma_f32 v[50:51], v[50:51], v[242:243], v[66:67] op_sel_hi:[1,0,1]
	v_pk_fma_f32 v[52:53], v[52:53], v[242:243], v[68:69] op_sel_hi:[1,0,1]
	v_pk_mul_f32 v[234:235], v[62:63], s[100:101] op_sel_hi:[1,0]
	v_pk_mul_f32 v[236:237], v[64:65], s[100:101] op_sel_hi:[1,0]
	v_exp_f32_e32 v234, v234
	v_exp_f32_e32 v235, v235
	v_exp_f32_e32 v236, v236
	v_exp_f32_e32 v237, v237
	v_pk_add_f32 v[234:235], v[234:235], 1.0 op_sel_hi:[1,0]
	v_pk_add_f32 v[236:237], v[236:237], 1.0 op_sel_hi:[1,0]
	v_rcp_f32_e32 v234, v234
	v_rcp_f32_e32 v235, v235
	v_rcp_f32_e32 v236, v236
	v_rcp_f32_e32 v237, v237
	v_pk_mul_f32 v[54:55], v[62:63], v[54:55]
	v_pk_mul_f32 v[56:57], v[64:65], v[56:57]
	v_pk_mul_f32 v[54:55], v[54:55], v[234:235]
	v_pk_mul_f32 v[56:57], v[56:57], v[236:237]
	v_cvt_pk_bf16_f32 v238, v54, v55
	v_cvt_pk_bf16_f32 v239, v56, v57
	v_pk_mul_f32 v[234:235], v[58:59], s[100:101] op_sel_hi:[1,0]
	v_pk_mul_f32 v[236:237], v[60:61], s[100:101] op_sel_hi:[1,0]
	v_exp_f32_e32 v234, v234
	v_exp_f32_e32 v235, v235
	v_exp_f32_e32 v236, v236
	v_exp_f32_e32 v237, v237
	v_pk_add_f32 v[234:235], v[234:235], 1.0 op_sel_hi:[1,0]
	v_pk_add_f32 v[236:237], v[236:237], 1.0 op_sel_hi:[1,0]
	v_rcp_f32_e32 v234, v234
	v_rcp_f32_e32 v235, v235
	v_rcp_f32_e32 v236, v236
	v_rcp_f32_e32 v237, v237
	v_pk_mul_f32 v[50:51], v[58:59], v[50:51]
	v_pk_mul_f32 v[52:53], v[60:61], v[52:53]
	v_pk_mul_f32 v[50:51], v[50:51], v[234:235]
	v_pk_mul_f32 v[52:53], v[52:53], v[236:237]
	v_cvt_pk_bf16_f32 v240, v50, v51
	v_cvt_pk_bf16_f32 v241, v52, v53
	global_store_dwordx4 v[86:87], v[238:241], off
	v_add_u32_e32 v51, 0x90, v180
	v_mad_i64_i32 v[52:53], s[2:3], v51, s46, v[162:163]
	v_lshl_add_u64 v[52:53], v[52:53], 0, v[164:165]
	v_pk_fma_f32 v[46:47], v[46:47], v[244:245], v[78:79] op_sel_hi:[1,0,1]
	v_pk_fma_f32 v[48:49], v[48:49], v[244:245], v[80:81] op_sel_hi:[1,0,1]
	v_pk_fma_f32 v[38:39], v[38:39], v[244:245], v[70:71] op_sel_hi:[1,0,1]
	v_pk_fma_f32 v[40:41], v[40:41], v[244:245], v[72:73] op_sel_hi:[1,0,1]
	v_pk_fma_f32 v[42:43], v[42:43], v[244:245], v[74:75] op_sel_hi:[1,0,1]
	v_pk_fma_f32 v[44:45], v[44:45], v[244:245], v[76:77] op_sel_hi:[1,0,1]
	v_pk_fma_f32 v[34:35], v[34:35], v[244:245], v[66:67] op_sel_hi:[1,0,1]
	v_pk_fma_f32 v[36:37], v[36:37], v[244:245], v[68:69] op_sel_hi:[1,0,1]
	v_pk_mul_f32 v[234:235], v[46:47], s[100:101] op_sel_hi:[1,0]
	v_pk_mul_f32 v[236:237], v[48:49], s[100:101] op_sel_hi:[1,0]
	v_exp_f32_e32 v234, v234
	v_exp_f32_e32 v235, v235
	v_exp_f32_e32 v236, v236
	v_exp_f32_e32 v237, v237
	v_pk_add_f32 v[234:235], v[234:235], 1.0 op_sel_hi:[1,0]
	v_pk_add_f32 v[236:237], v[236:237], 1.0 op_sel_hi:[1,0]
	v_rcp_f32_e32 v234, v234
	v_rcp_f32_e32 v235, v235
	v_rcp_f32_e32 v236, v236
	v_rcp_f32_e32 v237, v237
	v_pk_mul_f32 v[38:39], v[46:47], v[38:39]
	v_pk_mul_f32 v[40:41], v[48:49], v[40:41]
	v_pk_mul_f32 v[38:39], v[38:39], v[234:235]
	v_pk_mul_f32 v[40:41], v[40:41], v[236:237]
	v_cvt_pk_bf16_f32 v238, v38, v39
	v_cvt_pk_bf16_f32 v239, v40, v41
	v_pk_mul_f32 v[234:235], v[42:43], s[100:101] op_sel_hi:[1,0]
	v_pk_mul_f32 v[236:237], v[44:45], s[100:101] op_sel_hi:[1,0]
; __device__ __forceinline__ unsigned cvt_pk_bf16(float lo, float hi) { unsigned r; asm volatile("v_cvt_pk_bf16_f32 %0, %1, %2" : "=v"(r) : "v"(lo), "v"(hi)); return r; }
; __device__ __forceinline__ float silu_mul(float a, float b) { return a * b * __builtin_amdgcn_rcpf(1.0f + __builtin_amdgcn_exp2f(-a * LOG2E)); }
; #define PG8_BAR __builtin_amdgcn_s_barrier()
;     __device__ __forceinline__ void operator()(const f32x4 (&acc)[2][2][4][2], const Unit& u, int wr, int wc, int fr, int fq) const {
;     ...
;             for (int m = 0; m < 4; ++m) { const int row = row0 + ai * HALF + m * 16; const float rs = __shfl(ai ? rsl1 : rsl0, m * 16 + fr); bf16_t* rowp = O + (size_t)row * DFF + col0;
;                 const f32x4 a0 = acc[ai][0][m][0] * rs + ba0, a1 = acc[ai][0][m][1] * rs + ba1, b0 = acc[ai][1][m][0] * rs + bb0, b1 = acc[ai][1][m][1] * rs + bb1;
;                 u32x4 w; w.x = cvt_pk_bf16(silu_mul(a0[0], b0[0]), silu_mul(a0[1], b0[1])); w.y = cvt_pk_bf16(silu_mul(a0[2], b0[2]), silu_mul(a0[3], b0[3]));
;                 w.z = cvt_pk_bf16(silu_mul(a1[0], b1[0]), silu_mul(a1[1], b1[1])); w.w = cvt_pk_bf16(silu_mul(a1[2], b1[2]), silu_mul(a1[3], b1[3]));
;                 *(u32x4*)rowp = w; }
; template <class Epi, class Sched, bool ALIGN_EPI = false, bool SP2 = false>
; __device__ __forceinline__ void gemm_phase(LAS unsigned char* lds, const Gemm g, const Sched& S, const Epi& E) {
;     ...
;         if (!has_next) break;
; #pragma unroll
;         for (int a = 0; a < 2; ++a)
; #pragma unroll
;             for (int b = 0; b < 2; ++b)
; #pragma unroll
;                 for (int m = 0; m < 4; ++m)
; #pragma unroll
;                     for (int n = 0; n < 2; ++n) acc[a][b][m][n] = (f32x4){0.f, 0.f, 0.f, 0.f};
;         cur = nxt; cA = nA; cB = nB; ++ui;
;         if constexpr (ALIGN_EPI) { if (wr == 1) PG8_BAR; }
	v_exp_f32_e32 v234, v234
	v_exp_f32_e32 v235, v235
	v_exp_f32_e32 v236, v236
	v_exp_f32_e32 v237, v237
	v_pk_add_f32 v[234:235], v[234:235], 1.0 op_sel_hi:[1,0]
	v_pk_add_f32 v[236:237], v[236:237], 1.0 op_sel_hi:[1,0]
	v_rcp_f32_e32 v234, v234
	v_rcp_f32_e32 v235, v235
	v_rcp_f32_e32 v236, v236
	v_rcp_f32_e32 v237, v237
	v_pk_mul_f32 v[34:35], v[42:43], v[34:35]
	v_pk_mul_f32 v[36:37], v[44:45], v[36:37]
	v_pk_mul_f32 v[34:35], v[34:35], v[234:235]
	v_pk_mul_f32 v[36:37], v[36:37], v[236:237]
	v_cvt_pk_bf16_f32 v240, v34, v35
	v_cvt_pk_bf16_f32 v241, v36, v37
	global_store_dwordx4 v[52:53], v[238:241], off
	v_add_u32_e32 v35, 0xa0, v180
	v_mad_i64_i32 v[36:37], s[2:3], v35, s46, v[162:163]
	v_lshl_add_u64 v[36:37], v[36:37], 0, v[164:165]
	v_pk_fma_f32 v[30:31], v[30:31], v[246:247], v[78:79] op_sel_hi:[1,0,1]
	v_pk_fma_f32 v[32:33], v[32:33], v[246:247], v[80:81] op_sel_hi:[1,0,1]
	v_pk_fma_f32 v[22:23], v[22:23], v[246:247], v[70:71] op_sel_hi:[1,0,1]
	v_pk_fma_f32 v[24:25], v[24:25], v[246:247], v[72:73] op_sel_hi:[1,0,1]
	v_pk_fma_f32 v[26:27], v[26:27], v[246:247], v[74:75] op_sel_hi:[1,0,1]
	v_pk_fma_f32 v[28:29], v[28:29], v[246:247], v[76:77] op_sel_hi:[1,0,1]
	v_pk_fma_f32 v[18:19], v[18:19], v[246:247], v[66:67] op_sel_hi:[1,0,1]
	v_pk_fma_f32 v[20:21], v[20:21], v[246:247], v[68:69] op_sel_hi:[1,0,1]
	v_pk_mul_f32 v[234:235], v[30:31], s[100:101] op_sel_hi:[1,0]
	v_pk_mul_f32 v[236:237], v[32:33], s[100:101] op_sel_hi:[1,0]
	v_exp_f32_e32 v234, v234
	v_exp_f32_e32 v235, v235
	v_exp_f32_e32 v236, v236
	v_exp_f32_e32 v237, v237
	v_pk_add_f32 v[234:235], v[234:235], 1.0 op_sel_hi:[1,0]
	v_pk_add_f32 v[236:237], v[236:237], 1.0 op_sel_hi:[1,0]
	v_rcp_f32_e32 v234, v234
	v_rcp_f32_e32 v235, v235
	v_rcp_f32_e32 v236, v236
	v_rcp_f32_e32 v237, v237
	v_pk_mul_f32 v[22:23], v[30:31], v[22:23]
	v_pk_mul_f32 v[24:25], v[32:33], v[24:25]
	v_pk_mul_f32 v[22:23], v[22:23], v[234:235]
	v_pk_mul_f32 v[24:25], v[24:25], v[236:237]
	v_cvt_pk_bf16_f32 v238, v22, v23
	v_cvt_pk_bf16_f32 v239, v24, v25
	v_pk_mul_f32 v[234:235], v[26:27], s[100:101] op_sel_hi:[1,0]
	v_pk_mul_f32 v[236:237], v[28:29], s[100:101] op_sel_hi:[1,0]
	v_exp_f32_e32 v234, v234
	v_exp_f32_e32 v235, v235
	v_exp_f32_e32 v236, v236
	v_exp_f32_e32 v237, v237
	v_pk_add_f32 v[234:235], v[234:235], 1.0 op_sel_hi:[1,0]
	v_pk_add_f32 v[236:237], v[236:237], 1.0 op_sel_hi:[1,0]
	v_rcp_f32_e32 v234, v234
	v_rcp_f32_e32 v235, v235
	v_rcp_f32_e32 v236, v236
	v_rcp_f32_e32 v237, v237
	v_pk_mul_f32 v[18:19], v[26:27], v[18:19]
	v_pk_mul_f32 v[20:21], v[28:29], v[20:21]
	v_pk_mul_f32 v[18:19], v[18:19], v[234:235]
	v_pk_mul_f32 v[20:21], v[20:21], v[236:237]
	v_cvt_pk_bf16_f32 v240, v18, v19
	v_cvt_pk_bf16_f32 v241, v20, v21
	global_store_dwordx4 v[36:37], v[238:241], off
	v_add_u32_e32 v19, 0xb0, v180
	v_mad_i64_i32 v[20:21], s[2:3], v19, s46, v[162:163]
	v_lshl_add_u64 v[20:21], v[20:21], 0, v[164:165]
	s_mov_b64 s[2:3], -1
	v_pk_fma_f32 v[14:15], v[14:15], v[248:249], v[78:79] op_sel_hi:[1,0,1]
	v_pk_fma_f32 v[16:17], v[16:17], v[248:249], v[80:81] op_sel_hi:[1,0,1]
	v_pk_fma_f32 v[6:7], v[6:7], v[248:249], v[70:71] op_sel_hi:[1,0,1]
	v_pk_fma_f32 v[8:9], v[8:9], v[248:249], v[72:73] op_sel_hi:[1,0,1]
	v_pk_fma_f32 v[10:11], v[10:11], v[248:249], v[74:75] op_sel_hi:[1,0,1]
	v_pk_fma_f32 v[12:13], v[12:13], v[248:249], v[76:77] op_sel_hi:[1,0,1]
	v_pk_fma_f32 v[2:3], v[2:3], v[248:249], v[66:67] op_sel_hi:[1,0,1]
	v_pk_fma_f32 v[4:5], v[4:5], v[248:249], v[68:69] op_sel_hi:[1,0,1]
	v_pk_mul_f32 v[234:235], v[14:15], s[100:101] op_sel_hi:[1,0]
	v_pk_mul_f32 v[236:237], v[16:17], s[100:101] op_sel_hi:[1,0]
	v_exp_f32_e32 v234, v234
	v_exp_f32_e32 v235, v235
	v_exp_f32_e32 v236, v236
	v_exp_f32_e32 v237, v237
	v_pk_add_f32 v[234:235], v[234:235], 1.0 op_sel_hi:[1,0]
	v_pk_add_f32 v[236:237], v[236:237], 1.0 op_sel_hi:[1,0]
	v_rcp_f32_e32 v234, v234
	v_rcp_f32_e32 v235, v235
	v_rcp_f32_e32 v236, v236
	v_rcp_f32_e32 v237, v237
	v_pk_mul_f32 v[6:7], v[14:15], v[6:7]
	v_pk_mul_f32 v[8:9], v[16:17], v[8:9]
	v_pk_mul_f32 v[6:7], v[6:7], v[234:235]
	v_pk_mul_f32 v[8:9], v[8:9], v[236:237]
	v_cvt_pk_bf16_f32 v238, v6, v7
	v_cvt_pk_bf16_f32 v239, v8, v9
	v_pk_mul_f32 v[234:235], v[10:11], s[100:101] op_sel_hi:[1,0]
	v_pk_mul_f32 v[236:237], v[12:13], s[100:101] op_sel_hi:[1,0]
	v_exp_f32_e32 v234, v234
	v_exp_f32_e32 v235, v235
	v_exp_f32_e32 v236, v236
	v_exp_f32_e32 v237, v237
	v_pk_add_f32 v[234:235], v[234:235], 1.0 op_sel_hi:[1,0]
	v_pk_add_f32 v[236:237], v[236:237], 1.0 op_sel_hi:[1,0]
	v_rcp_f32_e32 v234, v234
	v_rcp_f32_e32 v235, v235
	v_rcp_f32_e32 v236, v236
	v_rcp_f32_e32 v237, v237
	v_pk_mul_f32 v[2:3], v[10:11], v[2:3]
	v_pk_mul_f32 v[4:5], v[12:13], v[4:5]
	v_pk_mul_f32 v[2:3], v[2:3], v[234:235]
	v_pk_mul_f32 v[4:5], v[4:5], v[236:237]
	v_cvt_pk_bf16_f32 v240, v2, v3
	v_cvt_pk_bf16_f32 v241, v4, v5
	global_store_dwordx4 v[20:21], v[238:241], off
	s_waitcnt vmcnt(8)
	s_setprio 0
	s_cbranch_vccz .LBB0_1818
	s_andn2_b64 vcc, exec, s[4:5]
	s_cbranch_vccnz .LBB0_1817
	s_barrier
	s_branch .LBB0_1817

; __device__ __forceinline__ unsigned cvt_pk_bf16(float lo, float hi) { unsigned r; asm volatile("v_cvt_pk_bf16_f32 %0, %1, %2" : "=v"(r) : "v"(lo), "v"(hi)); return r; }
; __device__ __forceinline__ float row_rstd(const float* ss, int row) { return 1.0f / sqrtf(ss[row] * (1.0f / DM) + 1e-6f); }
; __device__ __forceinline__ float silu_mul(float a, float b) { return a * b * __builtin_amdgcn_rcpf(1.0f + __builtin_amdgcn_exp2f(-a * LOG2E)); }
; #define PG8_BAR __builtin_amdgcn_s_barrier()
;     __device__ __forceinline__ void operator()(const f32x4 (&acc)[2][2][4][2], const Unit& u, int wr, int wc, int fr, int fq) const {
;         const int row0 = u.pm * BM + wr * 64 + fr, col0 = u.pn * HALF + wc * 32 + 8 * fq;
;         const int s = (u.pm < ML / BM) ? (u.pm >> 5) : 4;
;         const float* bp = bias + (size_t)s * BIAS_N + u.pn * BM + wc * 32 + 8 * fq;
;         const f32x4 ba0 = *(const f32x4*)bp, ba1 = *(const f32x4*)(bp + 4), bb0 = *(const f32x4*)(bp + HALF), bb1 = *(const f32x4*)(bp + HALF + 4);
;         const int lane = fq * 16 + fr;
;         const float rsl0 = row_rstd(ss, u.pm * BM + wr * 64 + lane), rsl1 = row_rstd(ss, u.pm * BM + HALF + wr * 64 + lane);
; #pragma unroll
;         for (int ai = 0; ai < 2; ++ai)
; #pragma unroll
;             for (int m = 0; m < 4; ++m) { const int row = row0 + ai * HALF + m * 16; const float rs = __shfl(ai ? rsl1 : rsl0, m * 16 + fr); bf16_t* rowp = O + (size_t)row * DFF + col0;
;                 const f32x4 a0 = acc[ai][0][m][0] * rs + ba0, a1 = acc[ai][0][m][1] * rs + ba1, b0 = acc[ai][1][m][0] * rs + bb0, b1 = acc[ai][1][m][1] * rs + bb1;
;                 u32x4 w; w.x = cvt_pk_bf16(silu_mul(a0[0], b0[0]), silu_mul(a0[1], b0[1])); w.y = cvt_pk_bf16(silu_mul(a0[2], b0[2]), silu_mul(a0[3], b0[3]));
;                 w.z = cvt_pk_bf16(silu_mul(a1[0], b1[0]), silu_mul(a1[1], b1[1])); w.w = cvt_pk_bf16(silu_mul(a1[2], b1[2]), silu_mul(a1[3], b1[3]));
;                 *(u32x4*)rowp = w; }
; template <class Epi, class Sched, bool ALIGN_EPI = false, bool SP2 = false>
; __device__ __forceinline__ void gemm_phase(LAS unsigned char* lds, const Gemm g, const Sched& S, const Epi& E) {
;     ...
;         if constexpr (ALIGN_EPI) { if (wr == 0) PG8_BAR; }
.LBB0_2921:
	s_lshl_b32 s2, s2, 8
	s_add_i32 s11, s2, s34
	s_lshl_b64 s[18:19], s[18:19], 2
	s_add_u32 s13, s35, s18
	s_addc_u32 s18, s38, s19
	s_lshl_b32 s2, s3, 8
	v_lshl_or_b32 v164, s3, 7, v172
	s_ashr_i32 s3, s2, 31
	s_lshl_b64 s[2:3], s[2:3], 2
	s_add_u32 s2, s13, s2
	s_addc_u32 s3, s18, s3
	v_or_b32_e32 v162, s11, v170
	s_add_u32 s2, s2, s44
	v_ashrrev_i32_e32 v163, 31, v162
	s_addc_u32 s3, s3, 0
	v_lshl_add_u64 v[162:163], v[162:163], 2, s[0:1]
	v_mov_b32_e32 v74, v234
	v_mov_b32_e32 v75, v235
	v_mov_b32_e32 v76, v236
	v_mov_b32_e32 v77, v237
	v_mov_b32_e32 v78, v238
	v_mov_b32_e32 v79, v239
	v_mov_b32_e32 v80, v240
	v_mov_b32_e32 v81, v241
	v_mov_b32_e32 v66, v242
	v_mov_b32_e32 v67, v243
	v_mov_b32_e32 v68, v244
	v_mov_b32_e32 v69, v245
	v_mov_b32_e32 v70, v246
	v_mov_b32_e32 v71, v247
	v_mov_b32_e32 v72, v248
	v_mov_b32_e32 v73, v249
	v_or_b32_e32 v180, s11, v1
	v_mov_b32_e32 v162, v250
	v_fmamk_f32 v162, v162, 0x3a000000, v177
	v_cmp_gt_f32_e32 vcc, s45, v162
	v_mul_f32_e32 v163, 0x4f800000, v162
	s_nop 0
	v_cndmask_b32_e32 v162, v162, v163, vcc
	v_sqrt_f32_e32 v163, v162
	s_nop 0
	v_add_u32_e32 v165, -1, v163
	v_fma_f32 v166, -v165, v163, v162
	v_cmp_ge_f32_e64 s[2:3], 0, v166
	v_add_u32_e32 v166, 1, v163
	s_nop 0
	v_cndmask_b32_e64 v165, v163, v165, s[2:3]
	v_fma_f32 v163, -v166, v163, v162
	v_cmp_lt_f32_e64 s[2:3], 0, v163
	s_nop 1
	v_cndmask_b32_e64 v163, v165, v166, s[2:3]
	v_mul_f32_e32 v165, 0x37800000, v163
	v_cndmask_b32_e32 v163, v163, v165, vcc
	v_cmp_class_f32_e32 vcc, v162, v178
	s_nop 1
	v_cndmask_b32_e32 v166, v163, v162, vcc
	v_add_u32_e32 v162, s11, v171
	v_ashrrev_i32_e32 v163, 31, v162
	v_lshl_add_u64 v[162:163], v[162:163], 2, s[0:1]
	v_mov_b32_e32 v162, v251
	v_fmamk_f32 v162, v162, 0x3a000000, v177
	v_cmp_gt_f32_e32 vcc, s45, v162
	v_mul_f32_e32 v163, 0x4f800000, v162
	s_nop 0
	v_cndmask_b32_e32 v162, v162, v163, vcc
	v_sqrt_f32_e32 v163, v162
	s_nop 0
	v_add_u32_e32 v165, -1, v163
	v_fma_f32 v167, -v165, v163, v162
	v_cmp_ge_f32_e64 s[2:3], 0, v167
	v_add_u32_e32 v167, 1, v163
	s_nop 0
	v_cndmask_b32_e64 v165, v163, v165, s[2:3]
	v_fma_f32 v163, -v167, v163, v162
	v_cmp_lt_f32_e64 s[2:3], 0, v163
	s_nop 1
	v_cndmask_b32_e64 v163, v165, v167, s[2:3]
	v_mul_f32_e32 v165, 0x37800000, v163
	v_cndmask_b32_e32 v163, v163, v165, vcc
	v_cmp_class_f32_e32 vcc, v162, v178
	v_ashrrev_i32_e32 v165, 31, v164
	v_lshlrev_b64 v[164:165], 1, v[164:165]
	v_cndmask_b32_e32 v181, v163, v162, vcc
	v_div_scale_f32 v162, s[2:3], v166, v166, 1.0
	v_rcp_f32_e32 v163, v162
	s_nop 0
	v_fma_f32 v167, -v162, v163, 1.0
	v_fmac_f32_e32 v163, v167, v163
	v_div_scale_f32 v167, vcc, 1.0, v166, 1.0
	v_mul_f32_e32 v168, v167, v163
	v_fma_f32 v182, -v162, v168, v167
	v_fmac_f32_e32 v168, v182, v163
	v_fma_f32 v162, -v162, v168, v167
	v_div_fmas_f32 v162, v162, v163, v168
	v_div_fixup_f32 v182, v162, v166, 1.0
	s_andn2_b64 vcc, exec, s[8:9]
	s_cbranch_vccnz .Lalign_2919
	s_barrier
	s_setprio 1
.Lalign_2919:
	s_mov_b32 s100, 0xbfb8aa3b
	ds_bpermute_b32 v242, v179, v182
	ds_bpermute_b32 v244, v179, v182 offset:64
	ds_bpermute_b32 v246, v179, v182 offset:128
	ds_bpermute_b32 v248, v179, v182 offset:192
	v_mov_b64_e32 v[162:163], s[96:97]
	v_mad_i64_i32 v[166:167], s[2:3], v180, s43, v[162:163]
	v_lshl_add_u64 v[166:167], v[166:167], 0, v[164:165]
	s_waitcnt lgkmcnt(0)
	v_pk_fma_f32 v[142:143], v[142:143], v[242:243], v[78:79] op_sel_hi:[1,0,1]
	v_pk_fma_f32 v[144:145], v[144:145], v[242:243], v[80:81] op_sel_hi:[1,0,1]
	v_pk_fma_f32 v[134:135], v[134:135], v[242:243], v[70:71] op_sel_hi:[1,0,1]
	v_pk_fma_f32 v[136:137], v[136:137], v[242:243], v[72:73] op_sel_hi:[1,0,1]
	v_pk_fma_f32 v[138:139], v[138:139], v[242:243], v[74:75] op_sel_hi:[1,0,1]
	v_pk_fma_f32 v[140:141], v[140:141], v[242:243], v[76:77] op_sel_hi:[1,0,1]
	v_pk_fma_f32 v[130:131], v[130:131], v[242:243], v[66:67] op_sel_hi:[1,0,1]
	v_pk_fma_f32 v[132:133], v[132:133], v[242:243], v[68:69] op_sel_hi:[1,0,1]
	v_pk_mul_f32 v[234:235], v[142:143], s[100:101] op_sel_hi:[1,0]
	v_pk_mul_f32 v[236:237], v[144:145], s[100:101] op_sel_hi:[1,0]
	v_exp_f32_e32 v234, v234
	v_exp_f32_e32 v235, v235
	v_exp_f32_e32 v236, v236
	v_exp_f32_e32 v237, v237
	v_pk_add_f32 v[234:235], v[234:235], 1.0 op_sel_hi:[1,0]
	v_pk_add_f32 v[236:237], v[236:237], 1.0 op_sel_hi:[1,0]
	v_rcp_f32_e32 v234, v234
	v_rcp_f32_e32 v235, v235
	v_rcp_f32_e32 v236, v236
	v_rcp_f32_e32 v237, v237
	v_pk_mul_f32 v[134:135], v[142:143], v[134:135]
	v_pk_mul_f32 v[136:137], v[144:145], v[136:137]
	v_pk_mul_f32 v[134:135], v[134:135], v[234:235]
	v_pk_mul_f32 v[136:137], v[136:137], v[236:237]
	v_cvt_pk_bf16_f32 v238, v134, v135
	v_cvt_pk_bf16_f32 v239, v136, v137
	v_pk_mul_f32 v[234:235], v[138:139], s[100:101] op_sel_hi:[1,0]
	v_pk_mul_f32 v[236:237], v[140:141], s[100:101] op_sel_hi:[1,0]
	v_exp_f32_e32 v234, v234
	v_exp_f32_e32 v235, v235
	v_exp_f32_e32 v236, v236
	v_exp_f32_e32 v237, v237
	v_pk_add_f32 v[234:235], v[234:235], 1.0 op_sel_hi:[1,0]
	v_pk_add_f32 v[236:237], v[236:237], 1.0 op_sel_hi:[1,0]
	v_rcp_f32_e32 v234, v234
	v_rcp_f32_e32 v235, v235
	v_rcp_f32_e32 v236, v236
	v_rcp_f32_e32 v237, v237
	v_pk_mul_f32 v[130:131], v[138:139], v[130:131]
	v_pk_mul_f32 v[132:133], v[140:141], v[132:133]
	v_pk_mul_f32 v[130:131], v[130:131], v[234:235]
	v_pk_mul_f32 v[132:133], v[132:133], v[236:237]
	v_cvt_pk_bf16_f32 v240, v130, v131
	v_cvt_pk_bf16_f32 v241, v132, v133
	global_store_dwordx4 v[166:167], v[238:241], off
	v_or_b32_e32 v131, 16, v180
	v_mad_i64_i32 v[132:133], s[2:3], v131, s43, v[162:163]
	v_lshl_add_u64 v[132:133], v[132:133], 0, v[164:165]
	v_pk_fma_f32 v[126:127], v[126:127], v[244:245], v[78:79] op_sel_hi:[1,0,1]
; __device__ __forceinline__ unsigned cvt_pk_bf16(float lo, float hi) { unsigned r; asm volatile("v_cvt_pk_bf16_f32 %0, %1, %2" : "=v"(r) : "v"(lo), "v"(hi)); return r; }
; __device__ __forceinline__ float silu_mul(float a, float b) { return a * b * __builtin_amdgcn_rcpf(1.0f + __builtin_amdgcn_exp2f(-a * LOG2E)); }
;     __device__ __forceinline__ void operator()(const f32x4 (&acc)[2][2][4][2], const Unit& u, int wr, int wc, int fr, int fq) const {
;     ...
;             for (int m = 0; m < 4; ++m) { const int row = row0 + ai * HALF + m * 16; const float rs = __shfl(ai ? rsl1 : rsl0, m * 16 + fr); bf16_t* rowp = O + (size_t)row * DFF + col0;
;                 const f32x4 a0 = acc[ai][0][m][0] * rs + ba0, a1 = acc[ai][0][m][1] * rs + ba1, b0 = acc[ai][1][m][0] * rs + bb0, b1 = acc[ai][1][m][1] * rs + bb1;
;                 u32x4 w; w.x = cvt_pk_bf16(silu_mul(a0[0], b0[0]), silu_mul(a0[1], b0[1])); w.y = cvt_pk_bf16(silu_mul(a0[2], b0[2]), silu_mul(a0[3], b0[3]));
;                 w.z = cvt_pk_bf16(silu_mul(a1[0], b1[0]), silu_mul(a1[1], b1[1])); w.w = cvt_pk_bf16(silu_mul(a1[2], b1[2]), silu_mul(a1[3], b1[3]));
;                 *(u32x4*)rowp = w; }
	v_pk_fma_f32 v[128:129], v[128:129], v[244:245], v[80:81] op_sel_hi:[1,0,1]
	v_pk_fma_f32 v[118:119], v[118:119], v[244:245], v[70:71] op_sel_hi:[1,0,1]
	v_pk_fma_f32 v[120:121], v[120:121], v[244:245], v[72:73] op_sel_hi:[1,0,1]
	v_pk_fma_f32 v[122:123], v[122:123], v[244:245], v[74:75] op_sel_hi:[1,0,1]
	v_pk_fma_f32 v[124:125], v[124:125], v[244:245], v[76:77] op_sel_hi:[1,0,1]
	v_pk_fma_f32 v[114:115], v[114:115], v[244:245], v[66:67] op_sel_hi:[1,0,1]
	v_pk_fma_f32 v[116:117], v[116:117], v[244:245], v[68:69] op_sel_hi:[1,0,1]
	v_pk_mul_f32 v[234:235], v[126:127], s[100:101] op_sel_hi:[1,0]
	v_pk_mul_f32 v[236:237], v[128:129], s[100:101] op_sel_hi:[1,0]
	v_exp_f32_e32 v234, v234
	v_exp_f32_e32 v235, v235
	v_exp_f32_e32 v236, v236
	v_exp_f32_e32 v237, v237
	v_pk_add_f32 v[234:235], v[234:235], 1.0 op_sel_hi:[1,0]
	v_pk_add_f32 v[236:237], v[236:237], 1.0 op_sel_hi:[1,0]
	v_rcp_f32_e32 v234, v234
	v_rcp_f32_e32 v235, v235
	v_rcp_f32_e32 v236, v236
	v_rcp_f32_e32 v237, v237
	v_pk_mul_f32 v[118:119], v[126:127], v[118:119]
	v_pk_mul_f32 v[120:121], v[128:129], v[120:121]
	v_pk_mul_f32 v[118:119], v[118:119], v[234:235]
	v_pk_mul_f32 v[120:121], v[120:121], v[236:237]
	v_cvt_pk_bf16_f32 v238, v118, v119
	v_cvt_pk_bf16_f32 v239, v120, v121
	v_pk_mul_f32 v[234:235], v[122:123], s[100:101] op_sel_hi:[1,0]
	v_pk_mul_f32 v[236:237], v[124:125], s[100:101] op_sel_hi:[1,0]
	v_exp_f32_e32 v234, v234
	v_exp_f32_e32 v235, v235
	v_exp_f32_e32 v236, v236
	v_exp_f32_e32 v237, v237
	v_pk_add_f32 v[234:235], v[234:235], 1.0 op_sel_hi:[1,0]
	v_pk_add_f32 v[236:237], v[236:237], 1.0 op_sel_hi:[1,0]
	v_rcp_f32_e32 v234, v234
	v_rcp_f32_e32 v235, v235
	v_rcp_f32_e32 v236, v236
	v_rcp_f32_e32 v237, v237
	v_pk_mul_f32 v[114:115], v[122:123], v[114:115]
	v_pk_mul_f32 v[116:117], v[124:125], v[116:117]
	v_pk_mul_f32 v[114:115], v[114:115], v[234:235]
	v_pk_mul_f32 v[116:117], v[116:117], v[236:237]
	v_cvt_pk_bf16_f32 v240, v114, v115
	v_cvt_pk_bf16_f32 v241, v116, v117
	global_store_dwordx4 v[132:133], v[238:241], off
	v_or_b32_e32 v115, 32, v180
	v_mad_i64_i32 v[116:117], s[2:3], v115, s43, v[162:163]
	v_lshl_add_u64 v[116:117], v[116:117], 0, v[164:165]
	v_pk_fma_f32 v[110:111], v[110:111], v[246:247], v[78:79] op_sel_hi:[1,0,1]
	v_pk_fma_f32 v[112:113], v[112:113], v[246:247], v[80:81] op_sel_hi:[1,0,1]
	v_pk_fma_f32 v[102:103], v[102:103], v[246:247], v[70:71] op_sel_hi:[1,0,1]
	v_pk_fma_f32 v[104:105], v[104:105], v[246:247], v[72:73] op_sel_hi:[1,0,1]
	v_pk_fma_f32 v[106:107], v[106:107], v[246:247], v[74:75] op_sel_hi:[1,0,1]
	v_pk_fma_f32 v[108:109], v[108:109], v[246:247], v[76:77] op_sel_hi:[1,0,1]
	v_pk_fma_f32 v[98:99], v[98:99], v[246:247], v[66:67] op_sel_hi:[1,0,1]
	v_pk_fma_f32 v[100:101], v[100:101], v[246:247], v[68:69] op_sel_hi:[1,0,1]
	v_pk_mul_f32 v[234:235], v[110:111], s[100:101] op_sel_hi:[1,0]
	v_pk_mul_f32 v[236:237], v[112:113], s[100:101] op_sel_hi:[1,0]
	v_exp_f32_e32 v234, v234
	v_exp_f32_e32 v235, v235
	v_exp_f32_e32 v236, v236
	v_exp_f32_e32 v237, v237
	v_pk_add_f32 v[234:235], v[234:235], 1.0 op_sel_hi:[1,0]
	v_pk_add_f32 v[236:237], v[236:237], 1.0 op_sel_hi:[1,0]
	v_rcp_f32_e32 v234, v234
	v_rcp_f32_e32 v235, v235
	v_rcp_f32_e32 v236, v236
	v_rcp_f32_e32 v237, v237
	v_pk_mul_f32 v[102:103], v[110:111], v[102:103]
	v_pk_mul_f32 v[104:105], v[112:113], v[104:105]
	v_pk_mul_f32 v[102:103], v[102:103], v[234:235]
	v_pk_mul_f32 v[104:105], v[104:105], v[236:237]
	v_cvt_pk_bf16_f32 v238, v102, v103
	v_cvt_pk_bf16_f32 v239, v104, v105
	v_pk_mul_f32 v[234:235], v[106:107], s[100:101] op_sel_hi:[1,0]
	v_pk_mul_f32 v[236:237], v[108:109], s[100:101] op_sel_hi:[1,0]
	v_exp_f32_e32 v234, v234
	v_exp_f32_e32 v235, v235
	v_exp_f32_e32 v236, v236
	v_exp_f32_e32 v237, v237
	v_pk_add_f32 v[234:235], v[234:235], 1.0 op_sel_hi:[1,0]
	v_pk_add_f32 v[236:237], v[236:237], 1.0 op_sel_hi:[1,0]
	v_rcp_f32_e32 v234, v234
	v_rcp_f32_e32 v235, v235
	v_rcp_f32_e32 v236, v236
	v_rcp_f32_e32 v237, v237
	v_pk_mul_f32 v[98:99], v[106:107], v[98:99]
	v_pk_mul_f32 v[100:101], v[108:109], v[100:101]
	v_pk_mul_f32 v[98:99], v[98:99], v[234:235]
	v_pk_mul_f32 v[100:101], v[100:101], v[236:237]
	v_cvt_pk_bf16_f32 v240, v98, v99
	v_cvt_pk_bf16_f32 v241, v100, v101
	global_store_dwordx4 v[116:117], v[238:241], off
	v_or_b32_e32 v99, 48, v180
	v_mad_i64_i32 v[100:101], s[2:3], v99, s43, v[162:163]
	v_lshl_add_u64 v[100:101], v[100:101], 0, v[164:165]
	v_pk_fma_f32 v[94:95], v[94:95], v[248:249], v[78:79] op_sel_hi:[1,0,1]
	v_pk_fma_f32 v[96:97], v[96:97], v[248:249], v[80:81] op_sel_hi:[1,0,1]
	v_pk_fma_f32 v[86:87], v[86:87], v[248:249], v[70:71] op_sel_hi:[1,0,1]
	v_pk_fma_f32 v[88:89], v[88:89], v[248:249], v[72:73] op_sel_hi:[1,0,1]
	v_pk_fma_f32 v[90:91], v[90:91], v[248:249], v[74:75] op_sel_hi:[1,0,1]
	v_pk_fma_f32 v[92:93], v[92:93], v[248:249], v[76:77] op_sel_hi:[1,0,1]
	v_pk_fma_f32 v[82:83], v[82:83], v[248:249], v[66:67] op_sel_hi:[1,0,1]
	v_pk_fma_f32 v[84:85], v[84:85], v[248:249], v[68:69] op_sel_hi:[1,0,1]
	v_pk_mul_f32 v[234:235], v[94:95], s[100:101] op_sel_hi:[1,0]
	v_pk_mul_f32 v[236:237], v[96:97], s[100:101] op_sel_hi:[1,0]
	v_exp_f32_e32 v234, v234
	v_exp_f32_e32 v235, v235
	v_exp_f32_e32 v236, v236
	v_exp_f32_e32 v237, v237
	v_pk_add_f32 v[234:235], v[234:235], 1.0 op_sel_hi:[1,0]
	v_pk_add_f32 v[236:237], v[236:237], 1.0 op_sel_hi:[1,0]
	v_rcp_f32_e32 v234, v234
	v_rcp_f32_e32 v235, v235
	v_rcp_f32_e32 v236, v236
	v_rcp_f32_e32 v237, v237
	v_pk_mul_f32 v[86:87], v[94:95], v[86:87]
	v_pk_mul_f32 v[88:89], v[96:97], v[88:89]
	v_pk_mul_f32 v[86:87], v[86:87], v[234:235]
	v_pk_mul_f32 v[88:89], v[88:89], v[236:237]
	v_cvt_pk_bf16_f32 v238, v86, v87
; __device__ __forceinline__ unsigned cvt_pk_bf16(float lo, float hi) { unsigned r; asm volatile("v_cvt_pk_bf16_f32 %0, %1, %2" : "=v"(r) : "v"(lo), "v"(hi)); return r; }
; __device__ __forceinline__ float row_rstd(const float* ss, int row) { return 1.0f / sqrtf(ss[row] * (1.0f / DM) + 1e-6f); }
; __device__ __forceinline__ float silu_mul(float a, float b) { return a * b * __builtin_amdgcn_rcpf(1.0f + __builtin_amdgcn_exp2f(-a * LOG2E)); }
;     __device__ __forceinline__ void operator()(const f32x4 (&acc)[2][2][4][2], const Unit& u, int wr, int wc, int fr, int fq) const {
;     ...
;         const float rsl0 = row_rstd(ss, u.pm * BM + wr * 64 + lane), rsl1 = row_rstd(ss, u.pm * BM + HALF + wr * 64 + lane);
; #pragma unroll
;         for (int ai = 0; ai < 2; ++ai)
; #pragma unroll
;             for (int m = 0; m < 4; ++m) { const int row = row0 + ai * HALF + m * 16; const float rs = __shfl(ai ? rsl1 : rsl0, m * 16 + fr); bf16_t* rowp = O + (size_t)row * DFF + col0;
;                 const f32x4 a0 = acc[ai][0][m][0] * rs + ba0, a1 = acc[ai][0][m][1] * rs + ba1, b0 = acc[ai][1][m][0] * rs + bb0, b1 = acc[ai][1][m][1] * rs + bb1;
;                 u32x4 w; w.x = cvt_pk_bf16(silu_mul(a0[0], b0[0]), silu_mul(a0[1], b0[1])); w.y = cvt_pk_bf16(silu_mul(a0[2], b0[2]), silu_mul(a0[3], b0[3]));
;                 w.z = cvt_pk_bf16(silu_mul(a1[0], b1[0]), silu_mul(a1[1], b1[1])); w.w = cvt_pk_bf16(silu_mul(a1[2], b1[2]), silu_mul(a1[3], b1[3]));
;                 *(u32x4*)rowp = w; }
	v_cvt_pk_bf16_f32 v239, v88, v89
	v_pk_mul_f32 v[234:235], v[90:91], s[100:101] op_sel_hi:[1,0]
	v_pk_mul_f32 v[236:237], v[92:93], s[100:101] op_sel_hi:[1,0]
	v_exp_f32_e32 v234, v234
	v_exp_f32_e32 v235, v235
	v_exp_f32_e32 v236, v236
	v_exp_f32_e32 v237, v237
	v_pk_add_f32 v[234:235], v[234:235], 1.0 op_sel_hi:[1,0]
	v_pk_add_f32 v[236:237], v[236:237], 1.0 op_sel_hi:[1,0]
	v_rcp_f32_e32 v234, v234
	v_rcp_f32_e32 v235, v235
	v_rcp_f32_e32 v236, v236
	v_rcp_f32_e32 v237, v237
	v_pk_mul_f32 v[82:83], v[90:91], v[82:83]
	v_pk_mul_f32 v[84:85], v[92:93], v[84:85]
	v_pk_mul_f32 v[82:83], v[82:83], v[234:235]
	v_pk_mul_f32 v[84:85], v[84:85], v[236:237]
	v_cvt_pk_bf16_f32 v240, v82, v83
	v_cvt_pk_bf16_f32 v241, v84, v85
	global_store_dwordx4 v[100:101], v[238:241], off
	s_nop 1
	v_div_scale_f32 v82, s[2:3], v181, v181, 1.0
	v_rcp_f32_e32 v84, v82
	v_add_u32_e32 v83, 0x80, v180
	v_fma_f32 v85, -v82, v84, 1.0
	v_fmac_f32_e32 v84, v85, v84
	v_div_scale_f32 v85, vcc, 1.0, v181, 1.0
	v_mul_f32_e32 v86, v85, v84
	v_fma_f32 v87, -v82, v86, v85
	v_fmac_f32_e32 v86, v87, v84
	v_fma_f32 v82, -v82, v86, v85
	v_div_fmas_f32 v82, v82, v84, v86
	v_div_fixup_f32 v82, v82, v181, 1.0
	ds_bpermute_b32 v242, v179, v82
	ds_bpermute_b32 v244, v179, v82 offset:64
	ds_bpermute_b32 v246, v179, v82 offset:128
	ds_bpermute_b32 v248, v179, v82 offset:192
	v_mad_i64_i32 v[86:87], s[2:3], v83, s43, v[162:163]
	v_lshl_add_u64 v[86:87], v[86:87], 0, v[164:165]
	s_and_b64 vcc, s[36:37], exec
	s_waitcnt lgkmcnt(0)
	v_pk_fma_f32 v[62:63], v[62:63], v[242:243], v[78:79] op_sel_hi:[1,0,1]
	v_pk_fma_f32 v[64:65], v[64:65], v[242:243], v[80:81] op_sel_hi:[1,0,1]
	v_pk_fma_f32 v[54:55], v[54:55], v[242:243], v[70:71] op_sel_hi:[1,0,1]
	v_pk_fma_f32 v[56:57], v[56:57], v[242:243], v[72:73] op_sel_hi:[1,0,1]
	v_pk_fma_f32 v[58:59], v[58:59], v[242:243], v[74:75] op_sel_hi:[1,0,1]
	v_pk_fma_f32 v[60:61], v[60:61], v[242:243], v[76:77] op_sel_hi:[1,0,1]
	v_pk_fma_f32 v[50:51], v[50:51], v[242:243], v[66:67] op_sel_hi:[1,0,1]
	v_pk_fma_f32 v[52:53], v[52:53], v[242:243], v[68:69] op_sel_hi:[1,0,1]
	v_pk_mul_f32 v[234:235], v[62:63], s[100:101] op_sel_hi:[1,0]
	v_pk_mul_f32 v[236:237], v[64:65], s[100:101] op_sel_hi:[1,0]
	v_exp_f32_e32 v234, v234
	v_exp_f32_e32 v235, v235
	v_exp_f32_e32 v236, v236
	v_exp_f32_e32 v237, v237
	v_pk_add_f32 v[234:235], v[234:235], 1.0 op_sel_hi:[1,0]
	v_pk_add_f32 v[236:237], v[236:237], 1.0 op_sel_hi:[1,0]
	v_rcp_f32_e32 v234, v234
	v_rcp_f32_e32 v235, v235
	v_rcp_f32_e32 v236, v236
	v_rcp_f32_e32 v237, v237
	v_pk_mul_f32 v[54:55], v[62:63], v[54:55]
	v_pk_mul_f32 v[56:57], v[64:65], v[56:57]
	v_pk_mul_f32 v[54:55], v[54:55], v[234:235]
	v_pk_mul_f32 v[56:57], v[56:57], v[236:237]
	v_cvt_pk_bf16_f32 v238, v54, v55
	v_cvt_pk_bf16_f32 v239, v56, v57
	v_pk_mul_f32 v[234:235], v[58:59], s[100:101] op_sel_hi:[1,0]
	v_pk_mul_f32 v[236:237], v[60:61], s[100:101] op_sel_hi:[1,0]
	v_exp_f32_e32 v234, v234
	v_exp_f32_e32 v235, v235
	v_exp_f32_e32 v236, v236
	v_exp_f32_e32 v237, v237
	v_pk_add_f32 v[234:235], v[234:235], 1.0 op_sel_hi:[1,0]
	v_pk_add_f32 v[236:237], v[236:237], 1.0 op_sel_hi:[1,0]
	v_rcp_f32_e32 v234, v234
	v_rcp_f32_e32 v235, v235
	v_rcp_f32_e32 v236, v236
	v_rcp_f32_e32 v237, v237
	v_pk_mul_f32 v[50:51], v[58:59], v[50:51]
	v_pk_mul_f32 v[52:53], v[60:61], v[52:53]
	v_pk_mul_f32 v[50:51], v[50:51], v[234:235]
	v_pk_mul_f32 v[52:53], v[52:53], v[236:237]
	v_cvt_pk_bf16_f32 v240, v50, v51
	v_cvt_pk_bf16_f32 v241, v52, v53
	global_store_dwordx4 v[86:87], v[238:241], off
	v_add_u32_e32 v51, 0x90, v180
	v_mad_i64_i32 v[52:53], s[2:3], v51, s43, v[162:163]
	v_lshl_add_u64 v[52:53], v[52:53], 0, v[164:165]
	v_pk_fma_f32 v[46:47], v[46:47], v[244:245], v[78:79] op_sel_hi:[1,0,1]
	v_pk_fma_f32 v[48:49], v[48:49], v[244:245], v[80:81] op_sel_hi:[1,0,1]
	v_pk_fma_f32 v[38:39], v[38:39], v[244:245], v[70:71] op_sel_hi:[1,0,1]
	v_pk_fma_f32 v[40:41], v[40:41], v[244:245], v[72:73] op_sel_hi:[1,0,1]
	v_pk_fma_f32 v[42:43], v[42:43], v[244:245], v[74:75] op_sel_hi:[1,0,1]
	v_pk_fma_f32 v[44:45], v[44:45], v[244:245], v[76:77] op_sel_hi:[1,0,1]
	v_pk_fma_f32 v[34:35], v[34:35], v[244:245], v[66:67] op_sel_hi:[1,0,1]
	v_pk_fma_f32 v[36:37], v[36:37], v[244:245], v[68:69] op_sel_hi:[1,0,1]
	v_pk_mul_f32 v[234:235], v[46:47], s[100:101] op_sel_hi:[1,0]
	v_pk_mul_f32 v[236:237], v[48:49], s[100:101] op_sel_hi:[1,0]
	v_exp_f32_e32 v234, v234
	v_exp_f32_e32 v235, v235
	v_exp_f32_e32 v236, v236
	v_exp_f32_e32 v237, v237
	v_pk_add_f32 v[234:235], v[234:235], 1.0 op_sel_hi:[1,0]
	v_pk_add_f32 v[236:237], v[236:237], 1.0 op_sel_hi:[1,0]
	v_rcp_f32_e32 v234, v234
	v_rcp_f32_e32 v235, v235
	v_rcp_f32_e32 v236, v236
	v_rcp_f32_e32 v237, v237
	v_pk_mul_f32 v[38:39], v[46:47], v[38:39]
	v_pk_mul_f32 v[40:41], v[48:49], v[40:41]
	v_pk_mul_f32 v[38:39], v[38:39], v[234:235]
	v_pk_mul_f32 v[40:41], v[40:41], v[236:237]
	v_cvt_pk_bf16_f32 v238, v38, v39
	v_cvt_pk_bf16_f32 v239, v40, v41
	v_pk_mul_f32 v[234:235], v[42:43], s[100:101] op_sel_hi:[1,0]
	v_pk_mul_f32 v[236:237], v[44:45], s[100:101] op_sel_hi:[1,0]
; __device__ __forceinline__ unsigned cvt_pk_bf16(float lo, float hi) { unsigned r; asm volatile("v_cvt_pk_bf16_f32 %0, %1, %2" : "=v"(r) : "v"(lo), "v"(hi)); return r; }
; __device__ __forceinline__ float silu_mul(float a, float b) { return a * b * __builtin_amdgcn_rcpf(1.0f + __builtin_amdgcn_exp2f(-a * LOG2E)); }
; #define PG8_BAR __builtin_amdgcn_s_barrier()
;     __device__ __forceinline__ void operator()(const f32x4 (&acc)[2][2][4][2], const Unit& u, int wr, int wc, int fr, int fq) const {
;     ...
;             for (int m = 0; m < 4; ++m) { const int row = row0 + ai * HALF + m * 16; const float rs = __shfl(ai ? rsl1 : rsl0, m * 16 + fr); bf16_t* rowp = O + (size_t)row * DFF + col0;
;                 const f32x4 a0 = acc[ai][0][m][0] * rs + ba0, a1 = acc[ai][0][m][1] * rs + ba1, b0 = acc[ai][1][m][0] * rs + bb0, b1 = acc[ai][1][m][1] * rs + bb1;
;                 u32x4 w; w.x = cvt_pk_bf16(silu_mul(a0[0], b0[0]), silu_mul(a0[1], b0[1])); w.y = cvt_pk_bf16(silu_mul(a0[2], b0[2]), silu_mul(a0[3], b0[3]));
;                 w.z = cvt_pk_bf16(silu_mul(a1[0], b1[0]), silu_mul(a1[1], b1[1])); w.w = cvt_pk_bf16(silu_mul(a1[2], b1[2]), silu_mul(a1[3], b1[3]));
;                 *(u32x4*)rowp = w; }
; template <class Epi, class Sched, bool ALIGN_EPI = false, bool SP2 = false>
; __device__ __forceinline__ void gemm_phase(LAS unsigned char* lds, const Gemm g, const Sched& S, const Epi& E) {
;     ...
;         if (!has_next) break;
; #pragma unroll
;         for (int a = 0; a < 2; ++a)
; #pragma unroll
;             for (int b = 0; b < 2; ++b)
; #pragma unroll
;                 for (int m = 0; m < 4; ++m)
; #pragma unroll
;                     for (int n = 0; n < 2; ++n) acc[a][b][m][n] = (f32x4){0.f, 0.f, 0.f, 0.f};
;         cur = nxt; cA = nA; cB = nB; ++ui;
;         if constexpr (ALIGN_EPI) { if (wr == 1) PG8_BAR; }
	v_exp_f32_e32 v234, v234
	v_exp_f32_e32 v235, v235
	v_exp_f32_e32 v236, v236
	v_exp_f32_e32 v237, v237
	v_pk_add_f32 v[234:235], v[234:235], 1.0 op_sel_hi:[1,0]
	v_pk_add_f32 v[236:237], v[236:237], 1.0 op_sel_hi:[1,0]
	v_rcp_f32_e32 v234, v234
	v_rcp_f32_e32 v235, v235
	v_rcp_f32_e32 v236, v236
	v_rcp_f32_e32 v237, v237
	v_pk_mul_f32 v[34:35], v[42:43], v[34:35]
	v_pk_mul_f32 v[36:37], v[44:45], v[36:37]
	v_pk_mul_f32 v[34:35], v[34:35], v[234:235]
	v_pk_mul_f32 v[36:37], v[36:37], v[236:237]
	v_cvt_pk_bf16_f32 v240, v34, v35
	v_cvt_pk_bf16_f32 v241, v36, v37
	global_store_dwordx4 v[52:53], v[238:241], off
	v_add_u32_e32 v35, 0xa0, v180
	v_mad_i64_i32 v[36:37], s[2:3], v35, s43, v[162:163]
	v_lshl_add_u64 v[36:37], v[36:37], 0, v[164:165]
	v_pk_fma_f32 v[30:31], v[30:31], v[246:247], v[78:79] op_sel_hi:[1,0,1]
	v_pk_fma_f32 v[32:33], v[32:33], v[246:247], v[80:81] op_sel_hi:[1,0,1]
	v_pk_fma_f32 v[22:23], v[22:23], v[246:247], v[70:71] op_sel_hi:[1,0,1]
	v_pk_fma_f32 v[24:25], v[24:25], v[246:247], v[72:73] op_sel_hi:[1,0,1]
	v_pk_fma_f32 v[26:27], v[26:27], v[246:247], v[74:75] op_sel_hi:[1,0,1]
	v_pk_fma_f32 v[28:29], v[28:29], v[246:247], v[76:77] op_sel_hi:[1,0,1]
	v_pk_fma_f32 v[18:19], v[18:19], v[246:247], v[66:67] op_sel_hi:[1,0,1]
	v_pk_fma_f32 v[20:21], v[20:21], v[246:247], v[68:69] op_sel_hi:[1,0,1]
	v_pk_mul_f32 v[234:235], v[30:31], s[100:101] op_sel_hi:[1,0]
	v_pk_mul_f32 v[236:237], v[32:33], s[100:101] op_sel_hi:[1,0]
	v_exp_f32_e32 v234, v234
	v_exp_f32_e32 v235, v235
	v_exp_f32_e32 v236, v236
	v_exp_f32_e32 v237, v237
	v_pk_add_f32 v[234:235], v[234:235], 1.0 op_sel_hi:[1,0]
	v_pk_add_f32 v[236:237], v[236:237], 1.0 op_sel_hi:[1,0]
	v_rcp_f32_e32 v234, v234
	v_rcp_f32_e32 v235, v235
	v_rcp_f32_e32 v236, v236
	v_rcp_f32_e32 v237, v237
	v_pk_mul_f32 v[22:23], v[30:31], v[22:23]
	v_pk_mul_f32 v[24:25], v[32:33], v[24:25]
	v_pk_mul_f32 v[22:23], v[22:23], v[234:235]
	v_pk_mul_f32 v[24:25], v[24:25], v[236:237]
	v_cvt_pk_bf16_f32 v238, v22, v23
	v_cvt_pk_bf16_f32 v239, v24, v25
	v_pk_mul_f32 v[234:235], v[26:27], s[100:101] op_sel_hi:[1,0]
	v_pk_mul_f32 v[236:237], v[28:29], s[100:101] op_sel_hi:[1,0]
	v_exp_f32_e32 v234, v234
	v_exp_f32_e32 v235, v235
	v_exp_f32_e32 v236, v236
	v_exp_f32_e32 v237, v237
	v_pk_add_f32 v[234:235], v[234:235], 1.0 op_sel_hi:[1,0]
	v_pk_add_f32 v[236:237], v[236:237], 1.0 op_sel_hi:[1,0]
	v_rcp_f32_e32 v234, v234
	v_rcp_f32_e32 v235, v235
	v_rcp_f32_e32 v236, v236
	v_rcp_f32_e32 v237, v237
	v_pk_mul_f32 v[18:19], v[26:27], v[18:19]
	v_pk_mul_f32 v[20:21], v[28:29], v[20:21]
	v_pk_mul_f32 v[18:19], v[18:19], v[234:235]
	v_pk_mul_f32 v[20:21], v[20:21], v[236:237]
	v_cvt_pk_bf16_f32 v240, v18, v19
	v_cvt_pk_bf16_f32 v241, v20, v21
	global_store_dwordx4 v[36:37], v[238:241], off
	v_add_u32_e32 v19, 0xb0, v180
	v_mad_i64_i32 v[20:21], s[2:3], v19, s43, v[162:163]
	v_lshl_add_u64 v[20:21], v[20:21], 0, v[164:165]
	s_mov_b64 s[2:3], -1
	v_pk_fma_f32 v[14:15], v[14:15], v[248:249], v[78:79] op_sel_hi:[1,0,1]
	v_pk_fma_f32 v[16:17], v[16:17], v[248:249], v[80:81] op_sel_hi:[1,0,1]
	v_pk_fma_f32 v[6:7], v[6:7], v[248:249], v[70:71] op_sel_hi:[1,0,1]
	v_pk_fma_f32 v[8:9], v[8:9], v[248:249], v[72:73] op_sel_hi:[1,0,1]
	v_pk_fma_f32 v[10:11], v[10:11], v[248:249], v[74:75] op_sel_hi:[1,0,1]
	v_pk_fma_f32 v[12:13], v[12:13], v[248:249], v[76:77] op_sel_hi:[1,0,1]
	v_pk_fma_f32 v[2:3], v[2:3], v[248:249], v[66:67] op_sel_hi:[1,0,1]
	v_pk_fma_f32 v[4:5], v[4:5], v[248:249], v[68:69] op_sel_hi:[1,0,1]
	v_pk_mul_f32 v[234:235], v[14:15], s[100:101] op_sel_hi:[1,0]
	v_pk_mul_f32 v[236:237], v[16:17], s[100:101] op_sel_hi:[1,0]
	v_exp_f32_e32 v234, v234
	v_exp_f32_e32 v235, v235
	v_exp_f32_e32 v236, v236
	v_exp_f32_e32 v237, v237
	v_pk_add_f32 v[234:235], v[234:235], 1.0 op_sel_hi:[1,0]
	v_pk_add_f32 v[236:237], v[236:237], 1.0 op_sel_hi:[1,0]
	v_rcp_f32_e32 v234, v234
	v_rcp_f32_e32 v235, v235
	v_rcp_f32_e32 v236, v236
	v_rcp_f32_e32 v237, v237
	v_pk_mul_f32 v[6:7], v[14:15], v[6:7]
	v_pk_mul_f32 v[8:9], v[16:17], v[8:9]
	v_pk_mul_f32 v[6:7], v[6:7], v[234:235]
	v_pk_mul_f32 v[8:9], v[8:9], v[236:237]
	v_cvt_pk_bf16_f32 v238, v6, v7
	v_cvt_pk_bf16_f32 v239, v8, v9
	v_pk_mul_f32 v[234:235], v[10:11], s[100:101] op_sel_hi:[1,0]
	v_pk_mul_f32 v[236:237], v[12:13], s[100:101] op_sel_hi:[1,0]
	v_exp_f32_e32 v234, v234
	v_exp_f32_e32 v235, v235
	v_exp_f32_e32 v236, v236
	v_exp_f32_e32 v237, v237
	v_pk_add_f32 v[234:235], v[234:235], 1.0 op_sel_hi:[1,0]
	v_pk_add_f32 v[236:237], v[236:237], 1.0 op_sel_hi:[1,0]
	v_rcp_f32_e32 v234, v234
	v_rcp_f32_e32 v235, v235
	v_rcp_f32_e32 v236, v236
	v_rcp_f32_e32 v237, v237
	v_pk_mul_f32 v[2:3], v[10:11], v[2:3]
	v_pk_mul_f32 v[4:5], v[12:13], v[4:5]
	v_pk_mul_f32 v[2:3], v[2:3], v[234:235]
	v_pk_mul_f32 v[4:5], v[4:5], v[236:237]
	v_cvt_pk_bf16_f32 v240, v2, v3
	v_cvt_pk_bf16_f32 v241, v4, v5
	global_store_dwordx4 v[20:21], v[238:241], off
	s_waitcnt vmcnt(8)
	s_setprio 0
	s_cbranch_vccz .LBB0_2912
	s_andn2_b64 vcc, exec, s[4:5]
	s_cbranch_vccnz .LBB0_2911
	s_barrier
	s_branch .LBB0_2911
